# speedup vs baseline: 1.0073x; 1.0038x over previous
;   #define LDA(dst,b,h) for(int m=0;m<4;++m)for(int k=0;k<2;++k) \
;     dst[m][k]=*reinterpret_cast<const bf16x8*>((char*)SA(b,h)+lds_byte(wr*64+m*16+fr,k*32+fq*8))
;   #define LDB(dst,b,h) for(int n=0;n<2;++n)for(int k=0;k<2;++k) \
;     dst[n][k]=*reinterpret_cast<const bf16x8*>((char*)SB(b,h)+lds_byte(wc*32+n*16+fr,k*32+fq*8))
;   #define MMA(ai,bj,At,Bt_) do{__builtin_amdgcn_s_setprio(1); \
;     for(int m=0;m<4;++m)for(int n=0;n<2;++n)for(int k=0;k<2;++k) \
;       acc[ai][bj][m][n]=__builtin_amdgcn_mfma_f32_16x16x32_bf16(Bt_[n][k],At[m][k],acc[ai][bj][m][n],0,0,0); \
;     __builtin_amdgcn_s_setprio(0);}while(0)
;   #define WAIT_V(n) asm volatile("s_waitcnt vmcnt(" #n ")":::"memory")
;   #define WAIT_L(n) asm volatile("s_waitcnt lgkmcnt(" #n ")":::"memory")
;   #define BAR __builtin_amdgcn_s_barrier()
;   #define SCHED __builtin_amdgcn_sched_barrier(0)
; template <bool TWO, class MID> ...
;     ...
;     LDB(B0,0,0); SCHED; LDA(At,0,0); STAGE_A(SA(1,1),1,t+1);
;     WAIT_L(8); BAR; WAIT_L(0); MMA(0,0,At,B0); BAR; SCHED;
;     LDB(B1,0,1); STAGE_B(SB(0,0),0,t+2);
;     BAR; WAIT_L(0); MMA(0,1,At,B1); BAR;
;     LDA(At,0,1); STAGE_A(SA(0,0),0,t+2);
;     BAR; WAIT_L(0); MMA(1,0,At,B0); BAR; SCHED;
;     STAGE_B(SB(0,1),1,t+2);
;     WAIT_V(6); BAR; MMA(1,1,At,B1); BAR;
.LBB0_169:
	ds_read_b128 v[170:173], v143
	ds_read_b128 v[174:177], v143 offset:1024
	ds_read_b128 v[178:181], v143 offset:2048
	ds_read_b128 v[182:185], v143 offset:3072
	ds_read_b128 v[186:189], v168
	ds_read_b128 v[190:193], v168 offset:1024
	ds_read_b128 v[196:199], v167
	ds_read_b128 v[200:203], v167 offset:1024
	ds_read_b128 v[204:207], v166
	ds_read_b128 v[208:211], v166 offset:1024
	ds_read_b128 v[212:215], v147
	ds_read_b128 v[216:219], v147 offset:1024
	s_add_u32 s17, s0, s12
	s_addc_u32 s18, s1, s13
	s_add_u32 m0, s98, 0xc000
	s_add_u32 s20, s17, 0x8080080
	s_addc_u32 s21, s18, 0
	global_load_lds_dwordx4 v132, s[20:21]
	s_add_u32 m0, s98, 0xe000
	s_setprio 1
	global_load_lds_dwordx4 v130, s[20:21]
	s_waitcnt lgkmcnt(8)
	s_barrier
	s_waitcnt lgkmcnt(0)
	v_mfma_f32_16x16x32_bf16 v[126:129], v[170:173], v[186:189], v[126:129]
	v_mfma_f32_16x16x32_bf16 v[122:125], v[178:181], v[186:189], v[122:125]
	v_mfma_f32_16x16x32_bf16 v[118:121], v[170:173], v[196:199], v[118:121]
	v_mfma_f32_16x16x32_bf16 v[114:117], v[178:181], v[196:199], v[114:117]
	v_mfma_f32_16x16x32_bf16 v[110:113], v[170:173], v[204:207], v[110:113]
	v_mfma_f32_16x16x32_bf16 v[106:109], v[178:181], v[204:207], v[106:109]
	v_mfma_f32_16x16x32_bf16 v[102:105], v[170:173], v[212:215], v[102:105]
	v_mfma_f32_16x16x32_bf16 v[98:101], v[178:181], v[212:215], v[98:101]
	v_mfma_f32_16x16x32_bf16 v[126:129], v[174:177], v[190:193], v[126:129]
	v_mfma_f32_16x16x32_bf16 v[122:125], v[182:185], v[190:193], v[122:125]
	v_mfma_f32_16x16x32_bf16 v[118:121], v[174:177], v[200:203], v[118:121]
	v_mfma_f32_16x16x32_bf16 v[114:117], v[182:185], v[200:203], v[114:117]
	v_mfma_f32_16x16x32_bf16 v[110:113], v[174:177], v[208:211], v[110:113]
	v_mfma_f32_16x16x32_bf16 v[106:109], v[182:185], v[208:211], v[106:109]
	v_mfma_f32_16x16x32_bf16 v[102:105], v[174:177], v[216:219], v[102:105]
	v_mfma_f32_16x16x32_bf16 v[98:101], v[182:185], v[216:219], v[98:101]
	s_barrier
	s_setprio 0
	s_add_u32 s19, s0, s14
	ds_read_b128 v[220:223], v141
	ds_read_b128 v[224:227], v141 offset:1024
	ds_read_b128 v[228:231], v141 offset:2048
	ds_read_b128 v[232:235], v141 offset:3072
	s_addc_u32 s20, s1, s15
	s_add_u32 m0, s98, 0x10000
	s_add_u32 s26, s19, 0x100
	s_addc_u32 s27, s20, 0
	global_load_lds_dwordx4 v132, s[26:27]
	s_add_u32 m0, s98, 0x12000
	s_setprio 1
	global_load_lds_dwordx4 v130, s[26:27]
	s_barrier
	s_waitcnt lgkmcnt(0)
	v_mfma_f32_16x16x32_bf16 v[94:97], v[220:223], v[186:189], v[94:97]
	v_mfma_f32_16x16x32_bf16 v[90:93], v[228:231], v[186:189], v[90:93]
	v_mfma_f32_16x16x32_bf16 v[86:89], v[220:223], v[196:199], v[86:89]
	v_mfma_f32_16x16x32_bf16 v[82:85], v[228:231], v[196:199], v[82:85]
	v_mfma_f32_16x16x32_bf16 v[78:81], v[220:223], v[204:207], v[78:81]
	v_mfma_f32_16x16x32_bf16 v[74:77], v[228:231], v[204:207], v[74:77]
	v_mfma_f32_16x16x32_bf16 v[70:73], v[220:223], v[212:215], v[70:73]
	v_mfma_f32_16x16x32_bf16 v[66:69], v[228:231], v[212:215], v[66:69]
	v_mfma_f32_16x16x32_bf16 v[94:97], v[224:227], v[190:193], v[94:97]
	v_mfma_f32_16x16x32_bf16 v[90:93], v[232:235], v[190:193], v[90:93]
	v_mfma_f32_16x16x32_bf16 v[86:89], v[224:227], v[200:203], v[86:89]
	v_mfma_f32_16x16x32_bf16 v[82:85], v[232:235], v[200:203], v[82:85]
	v_mfma_f32_16x16x32_bf16 v[78:81], v[224:227], v[208:211], v[78:81]
	v_mfma_f32_16x16x32_bf16 v[74:77], v[232:235], v[208:211], v[74:77]
	v_mfma_f32_16x16x32_bf16 v[70:73], v[224:227], v[216:219], v[70:73]
	v_mfma_f32_16x16x32_bf16 v[66:69], v[232:235], v[216:219], v[66:69]
	s_barrier
	s_setprio 0
	ds_read_b128 v[186:189], v168 offset:16384
	ds_read_b128 v[190:193], v168 offset:17408
	ds_read_b128 v[196:199], v167 offset:16384
	ds_read_b128 v[200:203], v167 offset:17408
	ds_read_b128 v[204:207], v166 offset:16384
	ds_read_b128 v[208:211], v166 offset:17408
	ds_read_b128 v[212:215], v147 offset:16384
	ds_read_b128 v[216:219], v147 offset:17408
	s_add_u32 m0, s98, 0x0
	s_add_u32 s26, s17, 0x8000100
	s_addc_u32 s27, s18, 0
	global_load_lds_dwordx4 v132, s[26:27]
	s_add_u32 m0, s98, 0x2000
	s_setprio 1
	global_load_lds_dwordx4 v130, s[26:27]
	s_barrier
	s_waitcnt lgkmcnt(0)
	v_mfma_f32_16x16x32_bf16 v[62:65], v[170:173], v[186:189], v[62:65]
	v_mfma_f32_16x16x32_bf16 v[58:61], v[178:181], v[186:189], v[58:61]
	v_mfma_f32_16x16x32_bf16 v[54:57], v[170:173], v[196:199], v[54:57]
	v_mfma_f32_16x16x32_bf16 v[50:53], v[178:181], v[196:199], v[50:53]
	v_mfma_f32_16x16x32_bf16 v[46:49], v[170:173], v[204:207], v[46:49]
	v_mfma_f32_16x16x32_bf16 v[42:45], v[178:181], v[204:207], v[42:45]
	v_mfma_f32_16x16x32_bf16 v[38:41], v[170:173], v[212:215], v[38:41]
	v_mfma_f32_16x16x32_bf16 v[34:37], v[178:181], v[212:215], v[34:37]
	v_mfma_f32_16x16x32_bf16 v[62:65], v[174:177], v[190:193], v[62:65]
	v_mfma_f32_16x16x32_bf16 v[58:61], v[182:185], v[190:193], v[58:61]
	v_mfma_f32_16x16x32_bf16 v[54:57], v[174:177], v[200:203], v[54:57]
	v_mfma_f32_16x16x32_bf16 v[50:53], v[182:185], v[200:203], v[50:53]
	v_mfma_f32_16x16x32_bf16 v[46:49], v[174:177], v[208:211], v[46:49]
	v_mfma_f32_16x16x32_bf16 v[42:45], v[182:185], v[208:211], v[42:45]
	v_mfma_f32_16x16x32_bf16 v[38:41], v[174:177], v[216:219], v[38:41]
	v_mfma_f32_16x16x32_bf16 v[34:37], v[182:185], v[216:219], v[34:37]
	s_barrier
	s_setprio 0
	s_add_u32 m0, s98, 0x14000
	s_add_u32 s26, s19, 0x80100
	s_addc_u32 s27, s20, 0
	global_load_lds_dwordx4 v132, s[26:27]
	s_add_u32 m0, s98, 0x16000
	s_setprio 1
	global_load_lds_dwordx4 v130, s[26:27]
	s_waitcnt vmcnt(6)
	s_barrier
;   #define LDA(dst,b,h) for(int m=0;m<4;++m)for(int k=0;k<2;++k) \
;     dst[m][k]=*reinterpret_cast<const bf16x8*>((char*)SA(b,h)+lds_byte(wr*64+m*16+fr,k*32+fq*8))
;   #define LDB(dst,b,h) for(int n=0;n<2;++n)for(int k=0;k<2;++k) \
;     dst[n][k]=*reinterpret_cast<const bf16x8*>((char*)SB(b,h)+lds_byte(wc*32+n*16+fr,k*32+fq*8))
;   #define MMA(ai,bj,At,Bt_) do{__builtin_amdgcn_s_setprio(1); \
;     for(int m=0;m<4;++m)for(int n=0;n<2;++n)for(int k=0;k<2;++k) \
;       acc[ai][bj][m][n]=__builtin_amdgcn_mfma_f32_16x16x32_bf16(Bt_[n][k],At[m][k],acc[ai][bj][m][n],0,0,0); \
;     __builtin_amdgcn_s_setprio(0);}while(0)
;   #define WAIT_V(n) asm volatile("s_waitcnt vmcnt(" #n ")":::"memory")
;   #define WAIT_L(n) asm volatile("s_waitcnt lgkmcnt(" #n ")":::"memory")
;   #define BAR __builtin_amdgcn_s_barrier()
;   #define SCHED __builtin_amdgcn_sched_barrier(0)
; template <bool TWO, class MID> ...
;     ...
;     WAIT_V(6); BAR; MMA(1,1,At,B1); BAR;
;     LDB(B0,1,0); SCHED; LDA(At,1,0); STAGE_A(SA(0,1),1,t+2);
;     WAIT_L(8); BAR; WAIT_L(0); MMA(0,0,At,B0); BAR; SCHED;
;     LDB(B1,1,1); STAGE_B(SB(1,0),0,t+3);
;     BAR; WAIT_L(0); MMA(0,1,At,B1); BAR;
;     LDA(At,1,1); STAGE_A(SA(1,0),0,t+3);
	v_mfma_f32_16x16x32_bf16 v[30:33], v[220:223], v[186:189], v[30:33]
	v_mfma_f32_16x16x32_bf16 v[26:29], v[228:231], v[186:189], v[26:29]
	v_mfma_f32_16x16x32_bf16 v[22:25], v[220:223], v[196:199], v[22:25]
	v_mfma_f32_16x16x32_bf16 v[18:21], v[228:231], v[196:199], v[18:21]
	v_mfma_f32_16x16x32_bf16 v[14:17], v[220:223], v[204:207], v[14:17]
	v_mfma_f32_16x16x32_bf16 v[10:13], v[228:231], v[204:207], v[10:13]
	v_mfma_f32_16x16x32_bf16 v[6:9], v[220:223], v[212:215], v[6:9]
	v_mfma_f32_16x16x32_bf16 v[2:5], v[228:231], v[212:215], v[2:5]
	v_mfma_f32_16x16x32_bf16 v[30:33], v[224:227], v[190:193], v[30:33]
	v_mfma_f32_16x16x32_bf16 v[26:29], v[232:235], v[190:193], v[26:29]
	v_mfma_f32_16x16x32_bf16 v[22:25], v[224:227], v[200:203], v[22:25]
	v_mfma_f32_16x16x32_bf16 v[18:21], v[232:235], v[200:203], v[18:21]
	v_mfma_f32_16x16x32_bf16 v[14:17], v[224:227], v[208:211], v[14:17]
	v_mfma_f32_16x16x32_bf16 v[10:13], v[232:235], v[208:211], v[10:13]
	v_mfma_f32_16x16x32_bf16 v[6:9], v[224:227], v[216:219], v[6:9]
	v_mfma_f32_16x16x32_bf16 v[2:5], v[232:235], v[216:219], v[2:5]
	s_barrier
	s_setprio 0
	ds_read_b128 v[170:173], v137
	ds_read_b128 v[174:177], v137 offset:1024
	ds_read_b128 v[178:181], v137 offset:2048
	ds_read_b128 v[182:185], v137 offset:3072
	ds_read_b128 v[186:189], v168 offset:32768
	ds_read_b128 v[190:193], v168 offset:33792
	ds_read_b128 v[196:199], v167 offset:32768
	ds_read_b128 v[200:203], v167 offset:33792
	ds_read_b128 v[204:207], v166 offset:32768
	ds_read_b128 v[208:211], v166 offset:33792
	ds_read_b128 v[212:215], v147 offset:32768
	ds_read_b128 v[216:219], v147 offset:33792
	s_add_u32 m0, s98, 0x4000
	s_add_u32 s26, s17, 0x8080100
	s_addc_u32 s27, s18, 0
	global_load_lds_dwordx4 v132, s[26:27]
	s_add_u32 m0, s98, 0x6000
	s_setprio 1
	global_load_lds_dwordx4 v130, s[26:27]
	s_waitcnt lgkmcnt(8)
	s_barrier
	s_waitcnt lgkmcnt(0)
	v_mfma_f32_16x16x32_bf16 v[126:129], v[170:173], v[186:189], v[126:129]
	v_mfma_f32_16x16x32_bf16 v[122:125], v[178:181], v[186:189], v[122:125]
	v_mfma_f32_16x16x32_bf16 v[118:121], v[170:173], v[196:199], v[118:121]
	v_mfma_f32_16x16x32_bf16 v[114:117], v[178:181], v[196:199], v[114:117]
	v_mfma_f32_16x16x32_bf16 v[110:113], v[170:173], v[204:207], v[110:113]
	v_mfma_f32_16x16x32_bf16 v[106:109], v[178:181], v[204:207], v[106:109]
	v_mfma_f32_16x16x32_bf16 v[102:105], v[170:173], v[212:215], v[102:105]
	v_mfma_f32_16x16x32_bf16 v[98:101], v[178:181], v[212:215], v[98:101]
	v_mfma_f32_16x16x32_bf16 v[126:129], v[174:177], v[190:193], v[126:129]
	v_mfma_f32_16x16x32_bf16 v[122:125], v[182:185], v[190:193], v[122:125]
	v_mfma_f32_16x16x32_bf16 v[118:121], v[174:177], v[200:203], v[118:121]
	v_mfma_f32_16x16x32_bf16 v[114:117], v[182:185], v[200:203], v[114:117]
	v_mfma_f32_16x16x32_bf16 v[110:113], v[174:177], v[208:211], v[110:113]
	v_mfma_f32_16x16x32_bf16 v[106:109], v[182:185], v[208:211], v[106:109]
	v_mfma_f32_16x16x32_bf16 v[102:105], v[174:177], v[216:219], v[102:105]
	v_mfma_f32_16x16x32_bf16 v[98:101], v[182:185], v[216:219], v[98:101]
	s_barrier
	s_setprio 0
	ds_read_b128 v[220:223], v135
	ds_read_b128 v[224:227], v135 offset:1024
	ds_read_b128 v[228:231], v135 offset:2048
	ds_read_b128 v[232:235], v135 offset:3072
	s_add_u32 m0, s98, 0x18000
	s_add_u32 s26, s19, 0x180
	s_addc_u32 s27, s20, 0
	global_load_lds_dwordx4 v132, s[26:27]
	s_add_u32 m0, s98, 0x1a000
	s_setprio 1
	global_load_lds_dwordx4 v130, s[26:27]
	s_barrier
	s_waitcnt lgkmcnt(0)
	v_mfma_f32_16x16x32_bf16 v[94:97], v[220:223], v[186:189], v[94:97]
	v_mfma_f32_16x16x32_bf16 v[90:93], v[228:231], v[186:189], v[90:93]
	v_mfma_f32_16x16x32_bf16 v[86:89], v[220:223], v[196:199], v[86:89]
	v_mfma_f32_16x16x32_bf16 v[82:85], v[228:231], v[196:199], v[82:85]
	v_mfma_f32_16x16x32_bf16 v[78:81], v[220:223], v[204:207], v[78:81]
	v_mfma_f32_16x16x32_bf16 v[74:77], v[228:231], v[204:207], v[74:77]
	v_mfma_f32_16x16x32_bf16 v[70:73], v[220:223], v[212:215], v[70:73]
	v_mfma_f32_16x16x32_bf16 v[66:69], v[228:231], v[212:215], v[66:69]
	v_mfma_f32_16x16x32_bf16 v[94:97], v[224:227], v[190:193], v[94:97]
	v_mfma_f32_16x16x32_bf16 v[90:93], v[232:235], v[190:193], v[90:93]
	v_mfma_f32_16x16x32_bf16 v[86:89], v[224:227], v[200:203], v[86:89]
	v_mfma_f32_16x16x32_bf16 v[82:85], v[232:235], v[200:203], v[82:85]
	v_mfma_f32_16x16x32_bf16 v[78:81], v[224:227], v[208:211], v[78:81]
	v_mfma_f32_16x16x32_bf16 v[74:77], v[232:235], v[208:211], v[74:77]
	v_mfma_f32_16x16x32_bf16 v[70:73], v[224:227], v[216:219], v[70:73]
	v_mfma_f32_16x16x32_bf16 v[66:69], v[232:235], v[216:219], v[66:69]
	s_barrier
	s_setprio 0
	ds_read_b128 v[186:189], v168 offset:49152
	ds_read_b128 v[190:193], v168 offset:50176
	ds_read_b128 v[196:199], v167 offset:49152
	ds_read_b128 v[200:203], v167 offset:50176
	ds_read_b128 v[204:207], v166 offset:49152
	ds_read_b128 v[208:211], v166 offset:50176
	ds_read_b128 v[212:215], v147 offset:49152
	ds_read_b128 v[216:219], v147 offset:50176
	s_add_u32 m0, s98, 0x8000
	s_add_u32 s26, s17, 0x8000180
	s_addc_u32 s27, s18, 0
	global_load_lds_dwordx4 v132, s[26:27]
	s_add_u32 m0, s98, 0xa000
	s_setprio 1
	global_load_lds_dwordx4 v130, s[26:27]
	s_barrier
;   #define LDA(dst,b,h) for(int m=0;m<4;++m)for(int k=0;k<2;++k) \
;     dst[m][k]=*reinterpret_cast<const bf16x8*>((char*)SA(b,h)+lds_byte(wr*64+m*16+fr,k*32+fq*8))
;   #define LDB(dst,b,h) for(int n=0;n<2;++n)for(int k=0;k<2;++k) \
;     dst[n][k]=*reinterpret_cast<const bf16x8*>((char*)SB(b,h)+lds_byte(wc*32+n*16+fr,k*32+fq*8))
;   #define MMA(ai,bj,At,Bt_) do{__builtin_amdgcn_s_setprio(1); \
;     for(int m=0;m<4;++m)for(int n=0;n<2;++n)for(int k=0;k<2;++k) \
;       acc[ai][bj][m][n]=__builtin_amdgcn_mfma_f32_16x16x32_bf16(Bt_[n][k],At[m][k],acc[ai][bj][m][n],0,0,0); \
;     __builtin_amdgcn_s_setprio(0);}while(0)
;   #define WAIT_V(n) asm volatile("s_waitcnt vmcnt(" #n ")":::"memory")
;   #define WAIT_L(n) asm volatile("s_waitcnt lgkmcnt(" #n ")":::"memory")
;   #define BAR __builtin_amdgcn_s_barrier()
;   #define SCHED __builtin_amdgcn_sched_barrier(0)
; template <bool TWO, class MID> ...
;     ...
;     LDA(At,1,1); STAGE_A(SA(1,0),0,t+3);
;     BAR; WAIT_L(0); MMA(1,0,At,B0); BAR; SCHED;
;     STAGE_B(SB(1,1),1,t+3);
;     WAIT_V(6); BAR; MMA(1,1,At,B1); BAR;
;   }
;   { LDB(B0,0,0); LDA(At,0,0); STAGE_A(SA(1,1),1,nt-1);
;     BAR; WAIT_L(0); MMA(0,0,At,B0); BAR;
;     LDB(B1,0,1); BAR; WAIT_L(0); MMA(0,1,At,B1); BAR;
	s_waitcnt lgkmcnt(0)
	v_mfma_f32_16x16x32_bf16 v[62:65], v[170:173], v[186:189], v[62:65]
	v_mfma_f32_16x16x32_bf16 v[58:61], v[178:181], v[186:189], v[58:61]
	v_mfma_f32_16x16x32_bf16 v[54:57], v[170:173], v[196:199], v[54:57]
	v_mfma_f32_16x16x32_bf16 v[50:53], v[178:181], v[196:199], v[50:53]
	v_mfma_f32_16x16x32_bf16 v[46:49], v[170:173], v[204:207], v[46:49]
	v_mfma_f32_16x16x32_bf16 v[42:45], v[178:181], v[204:207], v[42:45]
	v_mfma_f32_16x16x32_bf16 v[38:41], v[170:173], v[212:215], v[38:41]
	v_mfma_f32_16x16x32_bf16 v[34:37], v[178:181], v[212:215], v[34:37]
	v_mfma_f32_16x16x32_bf16 v[62:65], v[174:177], v[190:193], v[62:65]
	v_mfma_f32_16x16x32_bf16 v[58:61], v[182:185], v[190:193], v[58:61]
	v_mfma_f32_16x16x32_bf16 v[54:57], v[174:177], v[200:203], v[54:57]
	v_mfma_f32_16x16x32_bf16 v[50:53], v[182:185], v[200:203], v[50:53]
	v_mfma_f32_16x16x32_bf16 v[46:49], v[174:177], v[208:211], v[46:49]
	v_mfma_f32_16x16x32_bf16 v[42:45], v[182:185], v[208:211], v[42:45]
	v_mfma_f32_16x16x32_bf16 v[38:41], v[174:177], v[216:219], v[38:41]
	v_mfma_f32_16x16x32_bf16 v[34:37], v[182:185], v[216:219], v[34:37]
	s_barrier
	s_setprio 0
	s_add_u32 m0, s98, 0x1c000
	s_add_u32 s18, s19, 0x80180
	s_addc_u32 s19, s20, 0
	global_load_lds_dwordx4 v132, s[18:19]
	s_add_u32 m0, s98, 0x1e000
	s_setprio 1
	global_load_lds_dwordx4 v130, s[18:19]
	s_waitcnt vmcnt(6)
	s_barrier
	v_mfma_f32_16x16x32_bf16 v[30:33], v[220:223], v[186:189], v[30:33]
	v_mfma_f32_16x16x32_bf16 v[26:29], v[228:231], v[186:189], v[26:29]
	v_mfma_f32_16x16x32_bf16 v[22:25], v[220:223], v[196:199], v[22:25]
	v_mfma_f32_16x16x32_bf16 v[18:21], v[228:231], v[196:199], v[18:21]
	v_mfma_f32_16x16x32_bf16 v[14:17], v[220:223], v[204:207], v[14:17]
	v_mfma_f32_16x16x32_bf16 v[10:13], v[228:231], v[204:207], v[10:13]
	v_mfma_f32_16x16x32_bf16 v[6:9], v[220:223], v[212:215], v[6:9]
	v_mfma_f32_16x16x32_bf16 v[2:5], v[228:231], v[212:215], v[2:5]
	v_mfma_f32_16x16x32_bf16 v[30:33], v[224:227], v[190:193], v[30:33]
	v_mfma_f32_16x16x32_bf16 v[26:29], v[232:235], v[190:193], v[26:29]
	v_mfma_f32_16x16x32_bf16 v[22:25], v[224:227], v[200:203], v[22:25]
	v_mfma_f32_16x16x32_bf16 v[18:21], v[232:235], v[200:203], v[18:21]
	v_mfma_f32_16x16x32_bf16 v[14:17], v[224:227], v[208:211], v[14:17]
	v_mfma_f32_16x16x32_bf16 v[10:13], v[232:235], v[208:211], v[10:13]
	v_mfma_f32_16x16x32_bf16 v[6:9], v[224:227], v[216:219], v[6:9]
	v_mfma_f32_16x16x32_bf16 v[2:5], v[232:235], v[216:219], v[2:5]
	s_barrier
	s_setprio 0
	s_add_i32 s9, s9, 2
	s_add_u32 s0, s0, 0x100
	s_addc_u32 s1, s1, 0
	s_cmp_lt_u32 s9, 28
	s_cbranch_scc1 .LBB0_169
	ds_read_b128 v[150:153], v143
	ds_read_b128 v[158:161], v143 offset:1024
	ds_read_b128 v[162:165], v143 offset:2048
	ds_read_b128 v[142:145], v143 offset:3072
	ds_read_b128 v[170:173], v168
	ds_read_b128 v[174:177], v168 offset:1024
	ds_read_b128 v[178:181], v167
	ds_read_b128 v[182:185], v167 offset:1024
	ds_read_b128 v[186:189], v166
	ds_read_b128 v[190:193], v166 offset:1024
	ds_read_b128 v[196:199], v147
	ds_read_b128 v[200:203], v147 offset:1024
	s_add_u32 s0, s11, 0x80f80
	s_addc_u32 s1, s16, 0
	v_lshl_add_u64 v[132:133], s[0:1], 0, v[132:133]
	v_readfirstlane_b32 s9, v148
	s_mov_b32 m0, s9
	global_load_lds_dwordx4 v[132:133], off
	v_lshl_add_u64 v[130:131], s[0:1], 0, v[130:131]
	v_readfirstlane_b32 s0, v156
	s_mov_b32 m0, s0
	global_load_lds_dwordx4 v[130:131], off
	s_setprio 1
	s_barrier
	s_waitcnt lgkmcnt(0)
	v_mfma_f32_16x16x32_bf16 v[126:129], v[150:153], v[170:173], v[126:129]
	v_mfma_f32_16x16x32_bf16 v[122:125], v[162:165], v[170:173], v[122:125]
	v_mfma_f32_16x16x32_bf16 v[114:117], v[162:165], v[178:181], v[114:117]
	v_mfma_f32_16x16x32_bf16 v[106:109], v[162:165], v[186:189], v[106:109]
	v_mfma_f32_16x16x32_bf16 v[98:101], v[162:165], v[196:199], v[98:101]
	v_mfma_f32_16x16x32_bf16 v[126:129], v[158:161], v[174:177], v[126:129]
	v_mfma_f32_16x16x32_bf16 v[122:125], v[142:145], v[174:177], v[122:125]
	v_mfma_f32_16x16x32_bf16 v[118:121], v[150:153], v[178:181], v[118:121]
	v_mfma_f32_16x16x32_bf16 v[114:117], v[142:145], v[182:185], v[114:117]
	v_mfma_f32_16x16x32_bf16 v[110:113], v[150:153], v[186:189], v[110:113]
	v_mfma_f32_16x16x32_bf16 v[106:109], v[142:145], v[190:193], v[106:109]
	v_mfma_f32_16x16x32_bf16 v[102:105], v[150:153], v[196:199], v[102:105]
	v_mfma_f32_16x16x32_bf16 v[130:133], v[142:145], v[200:203], v[98:101]
	v_mfma_f32_16x16x32_bf16 v[118:121], v[158:161], v[182:185], v[118:121]
	v_mfma_f32_16x16x32_bf16 v[110:113], v[158:161], v[190:193], v[110:113]
	v_mfma_f32_16x16x32_bf16 v[102:105], v[158:161], v[200:203], v[102:105]
	s_barrier
	s_setprio 0
	ds_read_b128 v[98:101], v141
	ds_read_b128 v[154:157], v141 offset:1024
	ds_read_b128 v[204:207], v141 offset:2048
	ds_read_b128 v[138:141], v141 offset:3072
	s_setprio 1
	s_barrier
	s_waitcnt lgkmcnt(0)
	v_mfma_f32_16x16x32_bf16 v[86:89], v[98:101], v[178:181], v[86:89]
	v_mfma_f32_16x16x32_bf16 v[82:85], v[204:207], v[178:181], v[82:85]
	v_mfma_f32_16x16x32_bf16 v[70:73], v[98:101], v[196:199], v[70:73]
	v_mfma_f32_16x16x32_bf16 v[66:69], v[204:207], v[196:199], v[66:69]
	v_mfma_f32_16x16x32_bf16 v[94:97], v[98:101], v[170:173], v[94:97]
	v_mfma_f32_16x16x32_bf16 v[90:93], v[204:207], v[170:173], v[90:93]
	v_mfma_f32_16x16x32_bf16 v[86:89], v[154:157], v[182:185], v[86:89]
	v_mfma_f32_16x16x32_bf16 v[82:85], v[138:141], v[182:185], v[82:85]
	v_mfma_f32_16x16x32_bf16 v[78:81], v[98:101], v[186:189], v[78:81]
	v_mfma_f32_16x16x32_bf16 v[74:77], v[204:207], v[186:189], v[74:77]
	v_mfma_f32_16x16x32_bf16 v[70:73], v[154:157], v[200:203], v[70:73]
	v_mfma_f32_16x16x32_bf16 v[66:69], v[138:141], v[200:203], v[66:69]
	v_mfma_f32_16x16x32_bf16 v[94:97], v[154:157], v[174:177], v[94:97]
	v_mfma_f32_16x16x32_bf16 v[170:173], v[138:141], v[174:177], v[90:93]
	v_mfma_f32_16x16x32_bf16 v[174:177], v[154:157], v[190:193], v[78:81]
	v_mfma_f32_16x16x32_bf16 v[178:181], v[138:141], v[190:193], v[74:77]
	s_barrier
;   #define LDA(dst,b,h) for(int m=0;m<4;++m)for(int k=0;k<2;++k) \
;     dst[m][k]=*reinterpret_cast<const bf16x8*>((char*)SA(b,h)+lds_byte(wr*64+m*16+fr,k*32+fq*8))
;   #define LDB(dst,b,h) for(int n=0;n<2;++n)for(int k=0;k<2;++k) \
;     dst[n][k]=*reinterpret_cast<const bf16x8*>((char*)SB(b,h)+lds_byte(wc*32+n*16+fr,k*32+fq*8))
;   #define MMA(ai,bj,At,Bt_) do{__builtin_amdgcn_s_setprio(1); \
;     for(int m=0;m<4;++m)for(int n=0;n<2;++n)for(int k=0;k<2;++k) \
;       acc[ai][bj][m][n]=__builtin_amdgcn_mfma_f32_16x16x32_bf16(Bt_[n][k],At[m][k],acc[ai][bj][m][n],0,0,0); \
;     __builtin_amdgcn_s_setprio(0);}while(0)
;   #define WAIT_V(n) asm volatile("s_waitcnt vmcnt(" #n ")":::"memory")
;   #define WAIT_L(n) asm volatile("s_waitcnt lgkmcnt(" #n ")":::"memory")
;   #define BAR __builtin_amdgcn_s_barrier()
; template <bool TWO, class MID> ...
;     ...
;     LDA(At,0,1); WAIT_V(4); BAR; WAIT_L(0); MMA(1,0,At,B0); MMA(1,1,At,B1); BAR; }
;   { LDB(B0,1,0); LDA(At,1,0); WAIT_V(2); BAR; WAIT_L(0); MMA(0,0,At,B0); BAR;
	s_setprio 0
	s_nop 0
	ds_read_b128 v[74:77], v168 offset:16384
	ds_read_b128 v[78:81], v168 offset:17408
	ds_read_b128 v[90:93], v167 offset:16384
	ds_read_b128 v[182:185], v167 offset:17408
	ds_read_b128 v[186:189], v166 offset:16384
	ds_read_b128 v[190:193], v166 offset:17408
	ds_read_b128 v[196:199], v147 offset:16384
	ds_read_b128 v[200:203], v147 offset:17408
	s_waitcnt vmcnt(4)
	s_setprio 1
	s_barrier
	s_waitcnt lgkmcnt(0)
	v_mfma_f32_16x16x32_bf16 v[62:65], v[150:153], v[74:77], v[62:65]
	v_mfma_f32_16x16x32_bf16 v[58:61], v[162:165], v[74:77], v[58:61]
	v_mfma_f32_16x16x32_bf16 v[54:57], v[150:153], v[90:93], v[54:57]
	v_mfma_f32_16x16x32_bf16 v[50:53], v[162:165], v[90:93], v[50:53]
	v_mfma_f32_16x16x32_bf16 v[38:41], v[150:153], v[196:199], v[38:41]
	v_mfma_f32_16x16x32_bf16 v[34:37], v[162:165], v[196:199], v[34:37]
	v_mfma_f32_16x16x32_bf16 v[62:65], v[158:161], v[78:81], v[62:65]
	v_mfma_f32_16x16x32_bf16 v[58:61], v[142:145], v[78:81], v[58:61]
	v_mfma_f32_16x16x32_bf16 v[54:57], v[158:161], v[182:185], v[54:57]
	v_mfma_f32_16x16x32_bf16 v[50:53], v[142:145], v[182:185], v[50:53]
	v_mfma_f32_16x16x32_bf16 v[46:49], v[150:153], v[186:189], v[46:49]
	v_mfma_f32_16x16x32_bf16 v[42:45], v[162:165], v[186:189], v[42:45]
	v_mfma_f32_16x16x32_bf16 v[38:41], v[158:161], v[200:203], v[38:41]
	v_mfma_f32_16x16x32_bf16 v[34:37], v[142:145], v[200:203], v[34:37]
	v_mfma_f32_16x16x32_bf16 v[208:211], v[158:161], v[190:193], v[46:49]
	v_mfma_f32_16x16x32_bf16 v[212:215], v[142:145], v[190:193], v[42:45]
	s_setprio 0
	s_setprio 1
	v_mfma_f32_16x16x32_bf16 v[22:25], v[98:101], v[90:93], v[22:25]
	v_mfma_f32_16x16x32_bf16 v[18:21], v[204:207], v[90:93], v[18:21]
	v_mfma_f32_16x16x32_bf16 v[6:9], v[98:101], v[196:199], v[6:9]
	v_mfma_f32_16x16x32_bf16 v[2:5], v[204:207], v[196:199], v[2:5]
	v_mfma_f32_16x16x32_bf16 v[30:33], v[98:101], v[74:77], v[30:33]
	v_mfma_f32_16x16x32_bf16 v[26:29], v[204:207], v[74:77], v[26:29]
	v_mfma_f32_16x16x32_bf16 v[22:25], v[154:157], v[182:185], v[22:25]
	v_mfma_f32_16x16x32_bf16 v[18:21], v[138:141], v[182:185], v[18:21]
	v_mfma_f32_16x16x32_bf16 v[14:17], v[98:101], v[186:189], v[14:17]
	v_mfma_f32_16x16x32_bf16 v[10:13], v[204:207], v[186:189], v[10:13]
	v_mfma_f32_16x16x32_bf16 v[6:9], v[154:157], v[200:203], v[6:9]
	v_mfma_f32_16x16x32_bf16 v[2:5], v[138:141], v[200:203], v[2:5]
	v_mfma_f32_16x16x32_bf16 v[148:151], v[154:157], v[78:81], v[30:33]
	v_mfma_f32_16x16x32_bf16 v[158:161], v[138:141], v[78:81], v[26:29]
	v_mfma_f32_16x16x32_bf16 v[162:165], v[154:157], v[190:193], v[14:17]
	v_mfma_f32_16x16x32_bf16 v[182:185], v[138:141], v[190:193], v[10:13]
	s_barrier
	s_setprio 0
	s_nop 0
	ds_read_b128 v[10:13], v137
	ds_read_b128 v[14:17], v137 offset:1024
	ds_read_b128 v[152:155], v137 offset:2048
	ds_read_b128 v[186:189], v137 offset:3072
	ds_read_b128 v[26:29], v168 offset:32768
	ds_read_b128 v[30:33], v168 offset:33792
	ds_read_b128 v[42:45], v167 offset:32768
	ds_read_b128 v[46:49], v167 offset:33792
	ds_read_b128 v[190:193], v166 offset:32768
	ds_read_b128 v[196:199], v166 offset:33792
	ds_read_b128 v[200:203], v147 offset:32768
	ds_read_b128 v[204:207], v147 offset:33792
	s_waitcnt vmcnt(2)
	s_setprio 1
	s_barrier
	s_waitcnt lgkmcnt(0)
	v_mfma_f32_16x16x32_bf16 v[74:77], v[10:13], v[26:29], v[126:129]
	v_mfma_f32_16x16x32_bf16 v[142:145], v[14:17], v[30:33], v[74:77]
	v_mfma_f32_16x16x32_bf16 v[74:77], v[152:155], v[26:29], v[122:125]
	v_mfma_f32_16x16x32_bf16 v[138:141], v[186:189], v[30:33], v[74:77]
	v_mfma_f32_16x16x32_bf16 v[74:77], v[10:13], v[42:45], v[118:121]
	v_mfma_f32_16x16x32_bf16 v[126:129], v[14:17], v[46:49], v[74:77]
	v_mfma_f32_16x16x32_bf16 v[74:77], v[152:155], v[42:45], v[114:117]
	v_mfma_f32_16x16x32_bf16 v[122:125], v[186:189], v[46:49], v[74:77]
	v_mfma_f32_16x16x32_bf16 v[74:77], v[10:13], v[190:193], v[110:113]
	v_mfma_f32_16x16x32_bf16 v[98:101], v[14:17], v[196:199], v[74:77]
	v_mfma_f32_16x16x32_bf16 v[74:77], v[152:155], v[190:193], v[106:109]
	v_mfma_f32_16x16x32_bf16 v[90:93], v[186:189], v[196:199], v[74:77]
	v_mfma_f32_16x16x32_bf16 v[74:77], v[10:13], v[200:203], v[102:105]
	v_mfma_f32_16x16x32_bf16 v[78:81], v[14:17], v[204:207], v[74:77]
	v_mfma_f32_16x16x32_bf16 v[74:77], v[152:155], v[200:203], v[130:133]
	v_mfma_f32_16x16x32_bf16 v[74:77], v[186:189], v[204:207], v[74:77]
	s_barrier
;   #define LDA(dst,b,h) for(int m=0;m<4;++m)for(int k=0;k<2;++k) \
;     dst[m][k]=*reinterpret_cast<const bf16x8*>((char*)SA(b,h)+lds_byte(wr*64+m*16+fr,k*32+fq*8))
;   #define LDB(dst,b,h) for(int n=0;n<2;++n)for(int k=0;k<2;++k) \
;     dst[n][k]=*reinterpret_cast<const bf16x8*>((char*)SB(b,h)+lds_byte(wc*32+n*16+fr,k*32+fq*8))
;   #define MMA(ai,bj,At,Bt_) do{__builtin_amdgcn_s_setprio(1); \
;     for(int m=0;m<4;++m)for(int n=0;n<2;++n)for(int k=0;k<2;++k) \
;       acc[ai][bj][m][n]=__builtin_amdgcn_mfma_f32_16x16x32_bf16(Bt_[n][k],At[m][k],acc[ai][bj][m][n],0,0,0); \
;     __builtin_amdgcn_s_setprio(0);}while(0)
;   #define WAIT_V(n) asm volatile("s_waitcnt vmcnt(" #n ")":::"memory")
;   #define WAIT_L(n) asm volatile("s_waitcnt lgkmcnt(" #n ")":::"memory")
;   #define BAR __builtin_amdgcn_s_barrier()
; template <bool TWO, class MID> ...
;     ...
;     LDB(B1,1,1); WAIT_V(0); BAR; WAIT_L(0); MMA(0,1,At,B1); BAR;
;     LDA(At,1,1); BAR; WAIT_L(0); MMA(1,0,At,B0); MMA(1,1,At,B1); BAR; }
;   if(wr==0)BAR;
	s_setprio 0
	ds_read_b128 v[102:105], v135
	ds_read_b128 v[110:113], v135 offset:1024
	ds_read_b128 v[118:121], v135 offset:2048
	ds_read_b128 v[216:219], v135 offset:3072
	s_waitcnt vmcnt(0)
	s_setprio 1
	s_barrier
	s_waitcnt lgkmcnt(0)
	v_mfma_f32_16x16x32_bf16 v[94:97], v[102:105], v[26:29], v[94:97]
	v_mfma_f32_16x16x32_bf16 v[26:29], v[118:121], v[26:29], v[170:173]
	v_mfma_f32_16x16x32_bf16 v[130:133], v[216:219], v[30:33], v[26:29]
	v_mfma_f32_16x16x32_bf16 v[26:29], v[102:105], v[42:45], v[86:89]
	v_mfma_f32_16x16x32_bf16 v[114:117], v[110:113], v[46:49], v[26:29]
	v_mfma_f32_16x16x32_bf16 v[26:29], v[118:121], v[42:45], v[82:85]
	v_mfma_f32_16x16x32_bf16 v[106:109], v[216:219], v[46:49], v[26:29]
	v_mfma_f32_16x16x32_bf16 v[26:29], v[102:105], v[190:193], v[174:177]
	v_mfma_f32_16x16x32_bf16 v[86:89], v[110:113], v[196:199], v[26:29]
	v_mfma_f32_16x16x32_bf16 v[26:29], v[118:121], v[190:193], v[178:181]
	v_mfma_f32_16x16x32_bf16 v[82:85], v[216:219], v[196:199], v[26:29]
	v_mfma_f32_16x16x32_bf16 v[26:29], v[102:105], v[200:203], v[70:73]
	v_mfma_f32_16x16x32_bf16 v[70:73], v[110:113], v[204:207], v[26:29]
	v_mfma_f32_16x16x32_bf16 v[26:29], v[118:121], v[200:203], v[66:69]
	v_mfma_f32_16x16x32_bf16 v[134:137], v[110:113], v[30:33], v[94:97]
	v_mfma_f32_16x16x32_bf16 v[66:69], v[216:219], v[204:207], v[26:29]
	s_barrier
	s_setprio 0
	ds_read_b128 v[94:97], v168 offset:49152
	ds_read_b128 v[168:171], v168 offset:50176
	ds_read_b128 v[172:175], v167 offset:49152
	ds_read_b128 v[176:179], v167 offset:50176
	ds_read_b128 v[190:193], v166 offset:49152
	ds_read_b128 v[196:199], v166 offset:50176
	ds_read_b128 v[200:203], v147 offset:49152
	ds_read_b128 v[204:207], v147 offset:50176
	s_setprio 1
	s_barrier
	s_waitcnt lgkmcnt(0)
	v_mfma_f32_16x16x32_bf16 v[26:29], v[10:13], v[94:97], v[62:65]
	v_mfma_f32_16x16x32_bf16 v[62:65], v[14:17], v[168:171], v[26:29]
	v_mfma_f32_16x16x32_bf16 v[26:29], v[152:155], v[94:97], v[58:61]
	v_mfma_f32_16x16x32_bf16 v[58:61], v[186:189], v[168:171], v[26:29]
	v_mfma_f32_16x16x32_bf16 v[26:29], v[10:13], v[172:175], v[54:57]
	v_mfma_f32_16x16x32_bf16 v[46:49], v[14:17], v[176:179], v[26:29]
	v_mfma_f32_16x16x32_bf16 v[26:29], v[152:155], v[172:175], v[50:53]
	v_mfma_f32_16x16x32_bf16 v[42:45], v[186:189], v[176:179], v[26:29]
	v_mfma_f32_16x16x32_bf16 v[26:29], v[10:13], v[190:193], v[208:211]
	v_mfma_f32_16x16x32_bf16 v[10:13], v[10:13], v[200:203], v[38:41]
	v_mfma_f32_16x16x32_bf16 v[30:33], v[14:17], v[196:199], v[26:29]
	v_mfma_f32_16x16x32_bf16 v[26:29], v[152:155], v[190:193], v[212:215]
	v_mfma_f32_16x16x32_bf16 v[14:17], v[14:17], v[204:207], v[10:13]
	v_mfma_f32_16x16x32_bf16 v[10:13], v[152:155], v[200:203], v[34:37]
	v_mfma_f32_16x16x32_bf16 v[26:29], v[186:189], v[196:199], v[26:29]
	v_mfma_f32_16x16x32_bf16 v[10:13], v[186:189], v[204:207], v[10:13]
	s_setprio 0
	s_setprio 1
	v_mfma_f32_16x16x32_bf16 v[34:37], v[102:105], v[94:97], v[148:151]
	v_mfma_f32_16x16x32_bf16 v[54:57], v[110:113], v[168:171], v[34:37]
	v_mfma_f32_16x16x32_bf16 v[34:37], v[118:121], v[94:97], v[158:161]
	v_mfma_f32_16x16x32_bf16 v[18:21], v[118:121], v[172:175], v[18:21]
	v_mfma_f32_16x16x32_bf16 v[50:53], v[216:219], v[168:171], v[34:37]
	v_mfma_f32_16x16x32_bf16 v[22:25], v[102:105], v[172:175], v[22:25]
	v_mfma_f32_16x16x32_bf16 v[34:37], v[216:219], v[176:179], v[18:21]
	v_mfma_f32_16x16x32_bf16 v[18:21], v[102:105], v[190:193], v[162:165]
	v_mfma_f32_16x16x32_bf16 v[38:41], v[110:113], v[176:179], v[22:25]
	v_mfma_f32_16x16x32_bf16 v[22:25], v[110:113], v[196:199], v[18:21]
	v_mfma_f32_16x16x32_bf16 v[18:21], v[118:121], v[190:193], v[182:185]
	v_mfma_f32_16x16x32_bf16 v[6:9], v[102:105], v[200:203], v[6:9]
	v_mfma_f32_16x16x32_bf16 v[2:5], v[118:121], v[200:203], v[2:5]
	v_mfma_f32_16x16x32_bf16 v[18:21], v[216:219], v[196:199], v[18:21]
	v_mfma_f32_16x16x32_bf16 v[6:9], v[110:113], v[204:207], v[6:9]
	v_mfma_f32_16x16x32_bf16 v[2:5], v[216:219], v[204:207], v[2:5]
	s_setprio 0
	v_cmp_gt_u32_e32 vcc, s30, v1
	s_barrier
	s_and_saveexec_b64 s[0:1], vcc
	s_cbranch_execz .LBB0_172
	s_barrier

;   #define MMA(ai,bj,At,Bt_) do{__builtin_amdgcn_s_setprio(1); \
;     for(int m=0;m<4;++m)for(int n=0;n<2;++n)for(int k=0;k<2;++k) \
;       acc[ai][bj][m][n]=__builtin_amdgcn_mfma_f32_16x16x32_bf16(Bt_[n][k],At[m][k],acc[ai][bj][m][n],0,0,0); \
;     __builtin_amdgcn_s_setprio(0);}while(0)
;   #define WAIT_V(n) asm volatile("s_waitcnt vmcnt(" #n ")":::"memory")
;   #define BAR __builtin_amdgcn_s_barrier()
; template <bool TWO, class MID> ...
;     ...
;   for(int t=0;t<nt-2;t+=2){
;     if (TWO && t == nt1) mid();
;     ...
;     WAIT_V(6); BAR; MMA(1,1,At,B1); BAR;
;   }
.LBB0_437:
	s_waitcnt vmcnt(6)
	s_add_i32 s14, s26, 2
	s_setprio 1
	s_barrier
	v_mfma_f32_16x16x32_bf16 v[30:33], v[146:149], v[186:189], v[30:33]
	v_mfma_f32_16x16x32_bf16 v[26:29], v[154:157], v[186:189], v[26:29]
	v_mfma_f32_16x16x32_bf16 v[22:25], v[146:149], v[178:181], v[22:25]
	v_mfma_f32_16x16x32_bf16 v[18:21], v[154:157], v[178:181], v[18:21]
	v_mfma_f32_16x16x32_bf16 v[14:17], v[146:149], v[170:173], v[14:17]
	v_mfma_f32_16x16x32_bf16 v[10:13], v[154:157], v[170:173], v[10:13]
	v_mfma_f32_16x16x32_bf16 v[6:9], v[146:149], v[162:165], v[6:9]
	v_mfma_f32_16x16x32_bf16 v[2:5], v[154:157], v[162:165], v[2:5]
	v_mfma_f32_16x16x32_bf16 v[30:33], v[150:153], v[190:193], v[30:33]
	v_mfma_f32_16x16x32_bf16 v[26:29], v[158:161], v[190:193], v[26:29]
	v_mfma_f32_16x16x32_bf16 v[22:25], v[150:153], v[182:185], v[22:25]
	v_mfma_f32_16x16x32_bf16 v[18:21], v[158:161], v[182:185], v[18:21]
	v_mfma_f32_16x16x32_bf16 v[14:17], v[150:153], v[174:177], v[14:17]
	v_mfma_f32_16x16x32_bf16 v[10:13], v[158:161], v[174:177], v[10:13]
	v_mfma_f32_16x16x32_bf16 v[6:9], v[150:153], v[166:169], v[6:9]
	v_mfma_f32_16x16x32_bf16 v[2:5], v[158:161], v[166:169], v[2:5]
	s_barrier
	s_setprio 0
	s_add_u32 s12, s12, 0x100
	s_addc_u32 s13, s13, 0
	s_cmp_gt_u32 s26, 19
	s_cbranch_scc1 .LBB0_439
	s_mov_b32 s26, s14
	s_cmpk_lg_i32 s12, 0x400
	s_cbranch_scc0 .LBB0_404
	s_branch .LBB0_405

;   #define LDA(dst,b,h) for(int m=0;m<4;++m)for(int k=0;k<2;++k) \
;     dst[m][k]=*reinterpret_cast<const bf16x8*>((char*)SA(b,h)+lds_byte(wr*64+m*16+fr,k*32+fq*8))
;   #define LDB(dst,b,h) for(int n=0;n<2;++n)for(int k=0;k<2;++k) \
;     dst[n][k]=*reinterpret_cast<const bf16x8*>((char*)SB(b,h)+lds_byte(wc*32+n*16+fr,k*32+fq*8))
;   #define MMA(ai,bj,At,Bt_) do{__builtin_amdgcn_s_setprio(1); \
;     for(int m=0;m<4;++m)for(int n=0;n<2;++n)for(int k=0;k<2;++k) \
;       acc[ai][bj][m][n]=__builtin_amdgcn_mfma_f32_16x16x32_bf16(Bt_[n][k],At[m][k],acc[ai][bj][m][n],0,0,0); \
;     __builtin_amdgcn_s_setprio(0);}while(0)
;   #define WAIT_V(n) asm volatile("s_waitcnt vmcnt(" #n ")":::"memory")
;   #define WAIT_L(n) asm volatile("s_waitcnt lgkmcnt(" #n ")":::"memory")
;   #define BAR __builtin_amdgcn_s_barrier()
;   #define SCHED __builtin_amdgcn_sched_barrier(0)
; template <bool TWO, class MID> ...
;     ...
;     LDB(B0,0,0); SCHED; LDA(At,0,0); STAGE_A(SA(1,1),1,t+1);
;     WAIT_L(8); BAR; WAIT_L(0); MMA(0,0,At,B0); BAR; SCHED;
;     LDB(B1,0,1); STAGE_B(SB(0,0),0,t+2);
;     BAR; WAIT_L(0); MMA(0,1,At,B1); BAR;
;     LDA(At,0,1); STAGE_A(SA(0,0),0,t+2);
;     BAR; WAIT_L(0); MMA(1,0,At,B0); BAR; SCHED;
;     STAGE_B(SB(0,1),1,t+2);
;     WAIT_V(6); BAR; MMA(1,1,At,B1); BAR;
.LBB0_489:
	ds_read_b128 v[166:169], v149
	ds_read_b128 v[170:173], v149 offset:1024
	ds_read_b128 v[174:177], v149 offset:2048
	ds_read_b128 v[178:181], v149 offset:3072
	ds_read_b128 v[182:185], v141
	ds_read_b128 v[186:189], v141 offset:1024
	ds_read_b128 v[190:193], v139
	ds_read_b128 v[196:199], v139 offset:1024
	ds_read_b128 v[200:203], v137
	ds_read_b128 v[204:207], v137 offset:1024
	ds_read_b128 v[208:211], v135
	ds_read_b128 v[212:215], v135 offset:1024
	s_add_u32 s19, s4, s10
	s_addc_u32 s24, s5, s11
	s_add_u32 m0, s98, 0xc000
	s_add_u32 s26, s19, 0x36080080
	s_addc_u32 s27, s24, 0
	global_load_lds_dwordx4 v132, s[26:27]
	s_add_u32 m0, s98, 0xe000
	s_setprio 1
	global_load_lds_dwordx4 v130, s[26:27]
	s_waitcnt lgkmcnt(8)
	s_barrier
	s_waitcnt lgkmcnt(0)
	v_mfma_f32_16x16x32_bf16 v[126:129], v[166:169], v[182:185], v[126:129]
	v_mfma_f32_16x16x32_bf16 v[122:125], v[174:177], v[182:185], v[122:125]
	v_mfma_f32_16x16x32_bf16 v[118:121], v[166:169], v[190:193], v[118:121]
	v_mfma_f32_16x16x32_bf16 v[114:117], v[174:177], v[190:193], v[114:117]
	v_mfma_f32_16x16x32_bf16 v[110:113], v[166:169], v[200:203], v[110:113]
	v_mfma_f32_16x16x32_bf16 v[106:109], v[174:177], v[200:203], v[106:109]
	v_mfma_f32_16x16x32_bf16 v[102:105], v[166:169], v[208:211], v[102:105]
	v_mfma_f32_16x16x32_bf16 v[98:101], v[174:177], v[208:211], v[98:101]
	v_mfma_f32_16x16x32_bf16 v[126:129], v[170:173], v[186:189], v[126:129]
	v_mfma_f32_16x16x32_bf16 v[122:125], v[178:181], v[186:189], v[122:125]
	v_mfma_f32_16x16x32_bf16 v[118:121], v[170:173], v[196:199], v[118:121]
	v_mfma_f32_16x16x32_bf16 v[114:117], v[178:181], v[196:199], v[114:117]
	v_mfma_f32_16x16x32_bf16 v[110:113], v[170:173], v[204:207], v[110:113]
	v_mfma_f32_16x16x32_bf16 v[106:109], v[178:181], v[204:207], v[106:109]
	v_mfma_f32_16x16x32_bf16 v[102:105], v[170:173], v[212:215], v[102:105]
	v_mfma_f32_16x16x32_bf16 v[98:101], v[178:181], v[212:215], v[98:101]
	s_barrier
	s_setprio 0
	s_add_u32 s25, s4, s16
	ds_read_b128 v[216:219], v147
	ds_read_b128 v[220:223], v147 offset:1024
	ds_read_b128 v[224:227], v147 offset:2048
	ds_read_b128 v[228:231], v147 offset:3072
	s_addc_u32 s26, s5, s17
	s_add_u32 m0, s98, 0x10000
	s_add_u32 s28, s25, 0x3400100
	s_addc_u32 s29, s26, 0
	global_load_lds_dwordx4 v132, s[28:29]
	s_add_u32 m0, s98, 0x12000
	s_setprio 1
	global_load_lds_dwordx4 v130, s[28:29]
	s_barrier
	s_waitcnt lgkmcnt(0)
	v_mfma_f32_16x16x32_bf16 v[94:97], v[216:219], v[182:185], v[94:97]
	v_mfma_f32_16x16x32_bf16 v[90:93], v[224:227], v[182:185], v[90:93]
	v_mfma_f32_16x16x32_bf16 v[86:89], v[216:219], v[190:193], v[86:89]
	v_mfma_f32_16x16x32_bf16 v[82:85], v[224:227], v[190:193], v[82:85]
	v_mfma_f32_16x16x32_bf16 v[78:81], v[216:219], v[200:203], v[78:81]
	v_mfma_f32_16x16x32_bf16 v[74:77], v[224:227], v[200:203], v[74:77]
	v_mfma_f32_16x16x32_bf16 v[70:73], v[216:219], v[208:211], v[70:73]
	v_mfma_f32_16x16x32_bf16 v[66:69], v[224:227], v[208:211], v[66:69]
	v_mfma_f32_16x16x32_bf16 v[94:97], v[220:223], v[186:189], v[94:97]
	v_mfma_f32_16x16x32_bf16 v[90:93], v[228:231], v[186:189], v[90:93]
	v_mfma_f32_16x16x32_bf16 v[86:89], v[220:223], v[196:199], v[86:89]
	v_mfma_f32_16x16x32_bf16 v[82:85], v[228:231], v[196:199], v[82:85]
	v_mfma_f32_16x16x32_bf16 v[78:81], v[220:223], v[204:207], v[78:81]
	v_mfma_f32_16x16x32_bf16 v[74:77], v[228:231], v[204:207], v[74:77]
	v_mfma_f32_16x16x32_bf16 v[70:73], v[220:223], v[212:215], v[70:73]
	v_mfma_f32_16x16x32_bf16 v[66:69], v[228:231], v[212:215], v[66:69]
	s_barrier
	s_setprio 0
	ds_read_b128 v[182:185], v141 offset:16384
	ds_read_b128 v[186:189], v141 offset:17408
	ds_read_b128 v[190:193], v139 offset:16384
	ds_read_b128 v[196:199], v139 offset:17408
	ds_read_b128 v[200:203], v137 offset:16384
	ds_read_b128 v[204:207], v137 offset:17408
	ds_read_b128 v[208:211], v135 offset:16384
	ds_read_b128 v[212:215], v135 offset:17408
	s_add_u32 m0, s98, 0x0
	s_add_u32 s28, s19, 0x36000100
	s_addc_u32 s29, s24, 0
	global_load_lds_dwordx4 v132, s[28:29]
	s_add_u32 m0, s98, 0x2000
	s_setprio 1
	global_load_lds_dwordx4 v130, s[28:29]
	s_barrier
	s_waitcnt lgkmcnt(0)
	v_mfma_f32_16x16x32_bf16 v[62:65], v[166:169], v[182:185], v[62:65]
	v_mfma_f32_16x16x32_bf16 v[58:61], v[174:177], v[182:185], v[58:61]
	v_mfma_f32_16x16x32_bf16 v[54:57], v[166:169], v[190:193], v[54:57]
	v_mfma_f32_16x16x32_bf16 v[50:53], v[174:177], v[190:193], v[50:53]
	v_mfma_f32_16x16x32_bf16 v[46:49], v[166:169], v[200:203], v[46:49]
	v_mfma_f32_16x16x32_bf16 v[42:45], v[174:177], v[200:203], v[42:45]
	v_mfma_f32_16x16x32_bf16 v[38:41], v[166:169], v[208:211], v[38:41]
	v_mfma_f32_16x16x32_bf16 v[34:37], v[174:177], v[208:211], v[34:37]
	v_mfma_f32_16x16x32_bf16 v[62:65], v[170:173], v[186:189], v[62:65]
	v_mfma_f32_16x16x32_bf16 v[58:61], v[178:181], v[186:189], v[58:61]
	v_mfma_f32_16x16x32_bf16 v[54:57], v[170:173], v[196:199], v[54:57]
	v_mfma_f32_16x16x32_bf16 v[50:53], v[178:181], v[196:199], v[50:53]
	v_mfma_f32_16x16x32_bf16 v[46:49], v[170:173], v[204:207], v[46:49]
	v_mfma_f32_16x16x32_bf16 v[42:45], v[178:181], v[204:207], v[42:45]
	v_mfma_f32_16x16x32_bf16 v[38:41], v[170:173], v[212:215], v[38:41]
	v_mfma_f32_16x16x32_bf16 v[34:37], v[178:181], v[212:215], v[34:37]
	s_barrier
	s_setprio 0
	s_add_u32 m0, s98, 0x14000
	s_add_u32 s28, s25, 0x3480100
	s_addc_u32 s29, s26, 0
	global_load_lds_dwordx4 v132, s[28:29]
	s_add_u32 m0, s98, 0x16000
	s_setprio 1
	global_load_lds_dwordx4 v130, s[28:29]
	s_waitcnt vmcnt(6)
	s_barrier
;   #define LDA(dst,b,h) for(int m=0;m<4;++m)for(int k=0;k<2;++k) \
;     dst[m][k]=*reinterpret_cast<const bf16x8*>((char*)SA(b,h)+lds_byte(wr*64+m*16+fr,k*32+fq*8))
;   #define LDB(dst,b,h) for(int n=0;n<2;++n)for(int k=0;k<2;++k) \
;     dst[n][k]=*reinterpret_cast<const bf16x8*>((char*)SB(b,h)+lds_byte(wc*32+n*16+fr,k*32+fq*8))
;   #define MMA(ai,bj,At,Bt_) do{__builtin_amdgcn_s_setprio(1); \
;     for(int m=0;m<4;++m)for(int n=0;n<2;++n)for(int k=0;k<2;++k) \
;       acc[ai][bj][m][n]=__builtin_amdgcn_mfma_f32_16x16x32_bf16(Bt_[n][k],At[m][k],acc[ai][bj][m][n],0,0,0); \
;     __builtin_amdgcn_s_setprio(0);}while(0)
;   #define WAIT_V(n) asm volatile("s_waitcnt vmcnt(" #n ")":::"memory")
;   #define WAIT_L(n) asm volatile("s_waitcnt lgkmcnt(" #n ")":::"memory")
;   #define BAR __builtin_amdgcn_s_barrier()
;   #define SCHED __builtin_amdgcn_sched_barrier(0)
; template <bool TWO, class MID> ...
;     ...
;     WAIT_V(6); BAR; MMA(1,1,At,B1); BAR;
;     LDB(B0,1,0); SCHED; LDA(At,1,0); STAGE_A(SA(0,1),1,t+2);
;     WAIT_L(8); BAR; WAIT_L(0); MMA(0,0,At,B0); BAR; SCHED;
;     LDB(B1,1,1); STAGE_B(SB(1,0),0,t+3);
;     BAR; WAIT_L(0); MMA(0,1,At,B1); BAR;
;     LDA(At,1,1); STAGE_A(SA(1,0),0,t+3);
	v_mfma_f32_16x16x32_bf16 v[30:33], v[216:219], v[182:185], v[30:33]
	v_mfma_f32_16x16x32_bf16 v[26:29], v[224:227], v[182:185], v[26:29]
	v_mfma_f32_16x16x32_bf16 v[22:25], v[216:219], v[190:193], v[22:25]
	v_mfma_f32_16x16x32_bf16 v[18:21], v[224:227], v[190:193], v[18:21]
	v_mfma_f32_16x16x32_bf16 v[14:17], v[216:219], v[200:203], v[14:17]
	v_mfma_f32_16x16x32_bf16 v[10:13], v[224:227], v[200:203], v[10:13]
	v_mfma_f32_16x16x32_bf16 v[6:9], v[216:219], v[208:211], v[6:9]
	v_mfma_f32_16x16x32_bf16 v[2:5], v[224:227], v[208:211], v[2:5]
	v_mfma_f32_16x16x32_bf16 v[30:33], v[220:223], v[186:189], v[30:33]
	v_mfma_f32_16x16x32_bf16 v[26:29], v[228:231], v[186:189], v[26:29]
	v_mfma_f32_16x16x32_bf16 v[22:25], v[220:223], v[196:199], v[22:25]
	v_mfma_f32_16x16x32_bf16 v[18:21], v[228:231], v[196:199], v[18:21]
	v_mfma_f32_16x16x32_bf16 v[14:17], v[220:223], v[204:207], v[14:17]
	v_mfma_f32_16x16x32_bf16 v[10:13], v[228:231], v[204:207], v[10:13]
	v_mfma_f32_16x16x32_bf16 v[6:9], v[220:223], v[212:215], v[6:9]
	v_mfma_f32_16x16x32_bf16 v[2:5], v[228:231], v[212:215], v[2:5]
	s_barrier
	s_setprio 0
	ds_read_b128 v[166:169], v145
	ds_read_b128 v[170:173], v145 offset:1024
	ds_read_b128 v[174:177], v145 offset:2048
	ds_read_b128 v[178:181], v145 offset:3072
	ds_read_b128 v[182:185], v141 offset:32768
	ds_read_b128 v[186:189], v141 offset:33792
	ds_read_b128 v[190:193], v139 offset:32768
	ds_read_b128 v[196:199], v139 offset:33792
	ds_read_b128 v[200:203], v137 offset:32768
	ds_read_b128 v[204:207], v137 offset:33792
	ds_read_b128 v[208:211], v135 offset:32768
	ds_read_b128 v[212:215], v135 offset:33792
	s_add_u32 m0, s98, 0x4000
	s_add_u32 s28, s19, 0x36080100
	s_addc_u32 s29, s24, 0
	global_load_lds_dwordx4 v132, s[28:29]
	s_add_u32 m0, s98, 0x6000
	s_setprio 1
	global_load_lds_dwordx4 v130, s[28:29]
	s_waitcnt lgkmcnt(8)
	s_barrier
	s_waitcnt lgkmcnt(0)
	v_mfma_f32_16x16x32_bf16 v[126:129], v[166:169], v[182:185], v[126:129]
	v_mfma_f32_16x16x32_bf16 v[122:125], v[174:177], v[182:185], v[122:125]
	v_mfma_f32_16x16x32_bf16 v[118:121], v[166:169], v[190:193], v[118:121]
	v_mfma_f32_16x16x32_bf16 v[114:117], v[174:177], v[190:193], v[114:117]
	v_mfma_f32_16x16x32_bf16 v[110:113], v[166:169], v[200:203], v[110:113]
	v_mfma_f32_16x16x32_bf16 v[106:109], v[174:177], v[200:203], v[106:109]
	v_mfma_f32_16x16x32_bf16 v[102:105], v[166:169], v[208:211], v[102:105]
	v_mfma_f32_16x16x32_bf16 v[98:101], v[174:177], v[208:211], v[98:101]
	v_mfma_f32_16x16x32_bf16 v[126:129], v[170:173], v[186:189], v[126:129]
	v_mfma_f32_16x16x32_bf16 v[122:125], v[178:181], v[186:189], v[122:125]
	v_mfma_f32_16x16x32_bf16 v[118:121], v[170:173], v[196:199], v[118:121]
	v_mfma_f32_16x16x32_bf16 v[114:117], v[178:181], v[196:199], v[114:117]
	v_mfma_f32_16x16x32_bf16 v[110:113], v[170:173], v[204:207], v[110:113]
	v_mfma_f32_16x16x32_bf16 v[106:109], v[178:181], v[204:207], v[106:109]
	v_mfma_f32_16x16x32_bf16 v[102:105], v[170:173], v[212:215], v[102:105]
	v_mfma_f32_16x16x32_bf16 v[98:101], v[178:181], v[212:215], v[98:101]
	s_barrier
	s_setprio 0
	ds_read_b128 v[216:219], v143
	ds_read_b128 v[220:223], v143 offset:1024
	ds_read_b128 v[224:227], v143 offset:2048
	ds_read_b128 v[228:231], v143 offset:3072
	s_add_u32 m0, s98, 0x18000
	s_add_u32 s28, s25, 0x3400180
	s_addc_u32 s29, s26, 0
	global_load_lds_dwordx4 v132, s[28:29]
	s_add_u32 m0, s98, 0x1a000
	s_setprio 1
	global_load_lds_dwordx4 v130, s[28:29]
	s_barrier
	s_waitcnt lgkmcnt(0)
	v_mfma_f32_16x16x32_bf16 v[94:97], v[216:219], v[182:185], v[94:97]
	v_mfma_f32_16x16x32_bf16 v[90:93], v[224:227], v[182:185], v[90:93]
	v_mfma_f32_16x16x32_bf16 v[86:89], v[216:219], v[190:193], v[86:89]
	v_mfma_f32_16x16x32_bf16 v[82:85], v[224:227], v[190:193], v[82:85]
	v_mfma_f32_16x16x32_bf16 v[78:81], v[216:219], v[200:203], v[78:81]
	v_mfma_f32_16x16x32_bf16 v[74:77], v[224:227], v[200:203], v[74:77]
	v_mfma_f32_16x16x32_bf16 v[70:73], v[216:219], v[208:211], v[70:73]
	v_mfma_f32_16x16x32_bf16 v[66:69], v[224:227], v[208:211], v[66:69]
	v_mfma_f32_16x16x32_bf16 v[94:97], v[220:223], v[186:189], v[94:97]
	v_mfma_f32_16x16x32_bf16 v[90:93], v[228:231], v[186:189], v[90:93]
	v_mfma_f32_16x16x32_bf16 v[86:89], v[220:223], v[196:199], v[86:89]
	v_mfma_f32_16x16x32_bf16 v[82:85], v[228:231], v[196:199], v[82:85]
	v_mfma_f32_16x16x32_bf16 v[78:81], v[220:223], v[204:207], v[78:81]
	v_mfma_f32_16x16x32_bf16 v[74:77], v[228:231], v[204:207], v[74:77]
	v_mfma_f32_16x16x32_bf16 v[70:73], v[220:223], v[212:215], v[70:73]
	v_mfma_f32_16x16x32_bf16 v[66:69], v[228:231], v[212:215], v[66:69]
	s_barrier
	s_setprio 0
	ds_read_b128 v[182:185], v141 offset:49152
	ds_read_b128 v[186:189], v141 offset:50176
	ds_read_b128 v[190:193], v139 offset:49152
	ds_read_b128 v[196:199], v139 offset:50176
	ds_read_b128 v[200:203], v137 offset:49152
	ds_read_b128 v[204:207], v137 offset:50176
	ds_read_b128 v[208:211], v135 offset:49152
	ds_read_b128 v[212:215], v135 offset:50176
	s_add_u32 m0, s98, 0x8000
	s_add_u32 s28, s19, 0x36000180
	s_addc_u32 s29, s24, 0
	global_load_lds_dwordx4 v132, s[28:29]
	s_add_u32 m0, s98, 0xa000
	s_setprio 1
	global_load_lds_dwordx4 v130, s[28:29]
	s_barrier
;   #define LDA(dst,b,h) for(int m=0;m<4;++m)for(int k=0;k<2;++k) \
;     dst[m][k]=*reinterpret_cast<const bf16x8*>((char*)SA(b,h)+lds_byte(wr*64+m*16+fr,k*32+fq*8))
;   #define LDB(dst,b,h) for(int n=0;n<2;++n)for(int k=0;k<2;++k) \
;     dst[n][k]=*reinterpret_cast<const bf16x8*>((char*)SB(b,h)+lds_byte(wc*32+n*16+fr,k*32+fq*8))
;   #define MMA(ai,bj,At,Bt_) do{__builtin_amdgcn_s_setprio(1); \
;     for(int m=0;m<4;++m)for(int n=0;n<2;++n)for(int k=0;k<2;++k) \
;       acc[ai][bj][m][n]=__builtin_amdgcn_mfma_f32_16x16x32_bf16(Bt_[n][k],At[m][k],acc[ai][bj][m][n],0,0,0); \
;     __builtin_amdgcn_s_setprio(0);}while(0)
;   #define WAIT_V(n) asm volatile("s_waitcnt vmcnt(" #n ")":::"memory")
;   #define WAIT_L(n) asm volatile("s_waitcnt lgkmcnt(" #n ")":::"memory")
;   #define BAR __builtin_amdgcn_s_barrier()
;   #define SCHED __builtin_amdgcn_sched_barrier(0)
; template <bool TWO, class MID> ...
;     ...
;     BAR; WAIT_L(0); MMA(1,0,At,B0); BAR; SCHED;
;     STAGE_B(SB(1,1),1,t+3);
;     WAIT_V(6); BAR; MMA(1,1,At,B1); BAR;
;   }
;   { LDB(B0,0,0); LDA(At,0,0); STAGE_A(SA(1,1),1,nt-1);
;     BAR; WAIT_L(0); MMA(0,0,At,B0); BAR;
;     LDB(B1,0,1); BAR; WAIT_L(0); MMA(0,1,At,B1); BAR;
	s_waitcnt lgkmcnt(0)
	v_mfma_f32_16x16x32_bf16 v[62:65], v[166:169], v[182:185], v[62:65]
	v_mfma_f32_16x16x32_bf16 v[58:61], v[174:177], v[182:185], v[58:61]
	v_mfma_f32_16x16x32_bf16 v[54:57], v[166:169], v[190:193], v[54:57]
	v_mfma_f32_16x16x32_bf16 v[50:53], v[174:177], v[190:193], v[50:53]
	v_mfma_f32_16x16x32_bf16 v[46:49], v[166:169], v[200:203], v[46:49]
	v_mfma_f32_16x16x32_bf16 v[42:45], v[174:177], v[200:203], v[42:45]
	v_mfma_f32_16x16x32_bf16 v[38:41], v[166:169], v[208:211], v[38:41]
	v_mfma_f32_16x16x32_bf16 v[34:37], v[174:177], v[208:211], v[34:37]
	v_mfma_f32_16x16x32_bf16 v[62:65], v[170:173], v[186:189], v[62:65]
	v_mfma_f32_16x16x32_bf16 v[58:61], v[178:181], v[186:189], v[58:61]
	v_mfma_f32_16x16x32_bf16 v[54:57], v[170:173], v[196:199], v[54:57]
	v_mfma_f32_16x16x32_bf16 v[50:53], v[178:181], v[196:199], v[50:53]
	v_mfma_f32_16x16x32_bf16 v[46:49], v[170:173], v[204:207], v[46:49]
	v_mfma_f32_16x16x32_bf16 v[42:45], v[178:181], v[204:207], v[42:45]
	v_mfma_f32_16x16x32_bf16 v[38:41], v[170:173], v[212:215], v[38:41]
	v_mfma_f32_16x16x32_bf16 v[34:37], v[178:181], v[212:215], v[34:37]
	s_barrier
	s_setprio 0
	s_add_u32 m0, s98, 0x1c000
	s_add_u32 s24, s25, 0x3480180
	s_addc_u32 s25, s26, 0
	global_load_lds_dwordx4 v132, s[24:25]
	s_add_u32 m0, s98, 0x1e000
	s_setprio 1
	global_load_lds_dwordx4 v130, s[24:25]
	s_waitcnt vmcnt(6)
	s_barrier
	v_mfma_f32_16x16x32_bf16 v[30:33], v[216:219], v[182:185], v[30:33]
	v_mfma_f32_16x16x32_bf16 v[26:29], v[224:227], v[182:185], v[26:29]
	v_mfma_f32_16x16x32_bf16 v[22:25], v[216:219], v[190:193], v[22:25]
	v_mfma_f32_16x16x32_bf16 v[18:21], v[224:227], v[190:193], v[18:21]
	v_mfma_f32_16x16x32_bf16 v[14:17], v[216:219], v[200:203], v[14:17]
	v_mfma_f32_16x16x32_bf16 v[10:13], v[224:227], v[200:203], v[10:13]
	v_mfma_f32_16x16x32_bf16 v[6:9], v[216:219], v[208:211], v[6:9]
	v_mfma_f32_16x16x32_bf16 v[2:5], v[224:227], v[208:211], v[2:5]
	v_mfma_f32_16x16x32_bf16 v[30:33], v[220:223], v[186:189], v[30:33]
	v_mfma_f32_16x16x32_bf16 v[26:29], v[228:231], v[186:189], v[26:29]
	v_mfma_f32_16x16x32_bf16 v[22:25], v[220:223], v[196:199], v[22:25]
	v_mfma_f32_16x16x32_bf16 v[18:21], v[228:231], v[196:199], v[18:21]
	v_mfma_f32_16x16x32_bf16 v[14:17], v[220:223], v[204:207], v[14:17]
	v_mfma_f32_16x16x32_bf16 v[10:13], v[228:231], v[204:207], v[10:13]
	v_mfma_f32_16x16x32_bf16 v[6:9], v[220:223], v[212:215], v[6:9]
	v_mfma_f32_16x16x32_bf16 v[2:5], v[228:231], v[212:215], v[2:5]
	s_barrier
	s_setprio 0
	s_add_i32 s18, s18, 2
	s_add_u32 s4, s4, 0x100
	s_addc_u32 s5, s5, 0
	s_cmp_lt_u32 s18, 28
	s_cbranch_scc1 .LBB0_489
	ds_read_b128 v[152:155], v149
	ds_read_b128 v[156:159], v149 offset:1024
	ds_read_b128 v[160:163], v149 offset:2048
	ds_read_b128 v[164:167], v149 offset:3072
	ds_read_b128 v[168:171], v141
	ds_read_b128 v[172:175], v141 offset:1024
	ds_read_b128 v[176:179], v139
	ds_read_b128 v[180:183], v139 offset:1024
	ds_read_b128 v[184:187], v137
	ds_read_b128 v[188:191], v137 offset:1024
	ds_read_b128 v[196:199], v135
	ds_read_b128 v[200:203], v135 offset:1024
	s_add_u32 s4, s12, 0x80f80
	s_addc_u32 s5, s13, 0
	v_lshl_add_u64 v[132:133], s[4:5], 0, v[132:133]
	v_readfirstlane_b32 s12, v148
	s_mov_b32 m0, s12
	global_load_lds_dwordx4 v[132:133], off
	v_lshl_add_u64 v[130:131], s[4:5], 0, v[130:131]
	v_readfirstlane_b32 s4, v150
	s_mov_b32 m0, s4
	global_load_lds_dwordx4 v[130:131], off
	s_setprio 1
	s_barrier
	s_waitcnt lgkmcnt(0)
	v_mfma_f32_16x16x32_bf16 v[126:129], v[152:155], v[168:171], v[126:129]
	v_mfma_f32_16x16x32_bf16 v[122:125], v[160:163], v[168:171], v[122:125]
	v_mfma_f32_16x16x32_bf16 v[118:121], v[152:155], v[176:179], v[118:121]
	v_mfma_f32_16x16x32_bf16 v[114:117], v[160:163], v[176:179], v[114:117]
	v_mfma_f32_16x16x32_bf16 v[102:105], v[152:155], v[196:199], v[102:105]
	v_mfma_f32_16x16x32_bf16 v[98:101], v[160:163], v[196:199], v[98:101]
	v_mfma_f32_16x16x32_bf16 v[126:129], v[156:159], v[172:175], v[126:129]
	v_mfma_f32_16x16x32_bf16 v[122:125], v[164:167], v[172:175], v[122:125]
	v_mfma_f32_16x16x32_bf16 v[118:121], v[156:159], v[180:183], v[118:121]
	v_mfma_f32_16x16x32_bf16 v[114:117], v[164:167], v[180:183], v[114:117]
	v_mfma_f32_16x16x32_bf16 v[110:113], v[152:155], v[184:187], v[110:113]
	v_mfma_f32_16x16x32_bf16 v[106:109], v[160:163], v[184:187], v[106:109]
	v_mfma_f32_16x16x32_bf16 v[102:105], v[156:159], v[200:203], v[102:105]
	v_mfma_f32_16x16x32_bf16 v[98:101], v[164:167], v[200:203], v[98:101]
	v_mfma_f32_16x16x32_bf16 v[130:133], v[156:159], v[188:191], v[110:113]
	v_mfma_f32_16x16x32_bf16 v[148:151], v[164:167], v[188:191], v[106:109]
	s_barrier
	s_setprio 0
	s_nop 0
	ds_read_b128 v[106:109], v147
	ds_read_b128 v[110:113], v147 offset:1024
	ds_read_b128 v[204:207], v147 offset:2048
	ds_read_b128 v[208:211], v147 offset:3072
	s_setprio 1
	s_barrier
	s_waitcnt lgkmcnt(0)
	v_mfma_f32_16x16x32_bf16 v[86:89], v[106:109], v[176:179], v[86:89]
	v_mfma_f32_16x16x32_bf16 v[82:85], v[204:207], v[176:179], v[82:85]
	v_mfma_f32_16x16x32_bf16 v[70:73], v[106:109], v[196:199], v[70:73]
	v_mfma_f32_16x16x32_bf16 v[66:69], v[204:207], v[196:199], v[66:69]
	v_mfma_f32_16x16x32_bf16 v[94:97], v[106:109], v[168:171], v[94:97]
	v_mfma_f32_16x16x32_bf16 v[90:93], v[204:207], v[168:171], v[90:93]
	v_mfma_f32_16x16x32_bf16 v[86:89], v[110:113], v[180:183], v[86:89]
	v_mfma_f32_16x16x32_bf16 v[82:85], v[208:211], v[180:183], v[82:85]
	v_mfma_f32_16x16x32_bf16 v[78:81], v[106:109], v[184:187], v[78:81]
	v_mfma_f32_16x16x32_bf16 v[74:77], v[204:207], v[184:187], v[74:77]
	v_mfma_f32_16x16x32_bf16 v[70:73], v[110:113], v[200:203], v[70:73]
	v_mfma_f32_16x16x32_bf16 v[66:69], v[208:211], v[200:203], v[66:69]
	v_mfma_f32_16x16x32_bf16 v[212:215], v[110:113], v[172:175], v[94:97]
	v_mfma_f32_16x16x32_bf16 v[168:171], v[208:211], v[172:175], v[90:93]
	v_mfma_f32_16x16x32_bf16 v[172:175], v[110:113], v[188:191], v[78:81]
	v_mfma_f32_16x16x32_bf16 v[176:179], v[208:211], v[188:191], v[74:77]
	s_barrier
;   #define LDA(dst,b,h) for(int m=0;m<4;++m)for(int k=0;k<2;++k) \
;     dst[m][k]=*reinterpret_cast<const bf16x8*>((char*)SA(b,h)+lds_byte(wr*64+m*16+fr,k*32+fq*8))
;   #define LDB(dst,b,h) for(int n=0;n<2;++n)for(int k=0;k<2;++k) \
;     dst[n][k]=*reinterpret_cast<const bf16x8*>((char*)SB(b,h)+lds_byte(wc*32+n*16+fr,k*32+fq*8))
;   #define MMA(ai,bj,At,Bt_) do{__builtin_amdgcn_s_setprio(1); \
;     for(int m=0;m<4;++m)for(int n=0;n<2;++n)for(int k=0;k<2;++k) \
;       acc[ai][bj][m][n]=__builtin_amdgcn_mfma_f32_16x16x32_bf16(Bt_[n][k],At[m][k],acc[ai][bj][m][n],0,0,0); \
;     __builtin_amdgcn_s_setprio(0);}while(0)
;   #define WAIT_V(n) asm volatile("s_waitcnt vmcnt(" #n ")":::"memory")
;   #define WAIT_L(n) asm volatile("s_waitcnt lgkmcnt(" #n ")":::"memory")
;   #define BAR __builtin_amdgcn_s_barrier()
; template <bool TWO, class MID> ...
;     ...
;     LDA(At,0,1); WAIT_V(4); BAR; WAIT_L(0); MMA(1,0,At,B0); MMA(1,1,At,B1); BAR; }
;   { LDB(B0,1,0); LDA(At,1,0); WAIT_V(2); BAR; WAIT_L(0); MMA(0,0,At,B0); BAR;
	s_setprio 0
	s_nop 0
	ds_read_b128 v[74:77], v141 offset:16384
	ds_read_b128 v[78:81], v141 offset:17408
	ds_read_b128 v[90:93], v139 offset:16384
	ds_read_b128 v[94:97], v139 offset:17408
	ds_read_b128 v[180:183], v137 offset:16384
	ds_read_b128 v[184:187], v137 offset:17408
	ds_read_b128 v[188:191], v135 offset:16384
	ds_read_b128 v[196:199], v135 offset:17408
	s_waitcnt vmcnt(4)
	s_setprio 1
	s_barrier
	s_waitcnt lgkmcnt(0)
	v_mfma_f32_16x16x32_bf16 v[62:65], v[152:155], v[74:77], v[62:65]
	v_mfma_f32_16x16x32_bf16 v[58:61], v[160:163], v[74:77], v[58:61]
	v_mfma_f32_16x16x32_bf16 v[54:57], v[152:155], v[90:93], v[54:57]
	v_mfma_f32_16x16x32_bf16 v[50:53], v[160:163], v[90:93], v[50:53]
	v_mfma_f32_16x16x32_bf16 v[38:41], v[152:155], v[188:191], v[38:41]
	v_mfma_f32_16x16x32_bf16 v[34:37], v[160:163], v[188:191], v[34:37]
	v_mfma_f32_16x16x32_bf16 v[62:65], v[156:159], v[78:81], v[62:65]
	v_mfma_f32_16x16x32_bf16 v[58:61], v[164:167], v[78:81], v[58:61]
	v_mfma_f32_16x16x32_bf16 v[54:57], v[156:159], v[94:97], v[54:57]
	v_mfma_f32_16x16x32_bf16 v[50:53], v[164:167], v[94:97], v[50:53]
	v_mfma_f32_16x16x32_bf16 v[46:49], v[152:155], v[180:183], v[46:49]
	v_mfma_f32_16x16x32_bf16 v[42:45], v[160:163], v[180:183], v[42:45]
	v_mfma_f32_16x16x32_bf16 v[38:41], v[156:159], v[196:199], v[38:41]
	v_mfma_f32_16x16x32_bf16 v[34:37], v[164:167], v[196:199], v[34:37]
	v_mfma_f32_16x16x32_bf16 v[200:203], v[156:159], v[184:187], v[46:49]
	v_mfma_f32_16x16x32_bf16 v[216:219], v[164:167], v[184:187], v[42:45]
	s_setprio 0
	s_setprio 1
	v_mfma_f32_16x16x32_bf16 v[22:25], v[106:109], v[90:93], v[22:25]
	v_mfma_f32_16x16x32_bf16 v[18:21], v[204:207], v[90:93], v[18:21]
	v_mfma_f32_16x16x32_bf16 v[6:9], v[106:109], v[188:191], v[6:9]
	v_mfma_f32_16x16x32_bf16 v[2:5], v[204:207], v[188:191], v[2:5]
	v_mfma_f32_16x16x32_bf16 v[30:33], v[106:109], v[74:77], v[30:33]
	v_mfma_f32_16x16x32_bf16 v[26:29], v[204:207], v[74:77], v[26:29]
	v_mfma_f32_16x16x32_bf16 v[22:25], v[110:113], v[94:97], v[22:25]
	v_mfma_f32_16x16x32_bf16 v[18:21], v[208:211], v[94:97], v[18:21]
	v_mfma_f32_16x16x32_bf16 v[14:17], v[106:109], v[180:183], v[14:17]
	v_mfma_f32_16x16x32_bf16 v[10:13], v[204:207], v[180:183], v[10:13]
	v_mfma_f32_16x16x32_bf16 v[6:9], v[110:113], v[196:199], v[6:9]
	v_mfma_f32_16x16x32_bf16 v[2:5], v[208:211], v[196:199], v[2:5]
	v_mfma_f32_16x16x32_bf16 v[152:155], v[110:113], v[78:81], v[30:33]
	v_mfma_f32_16x16x32_bf16 v[156:159], v[208:211], v[78:81], v[26:29]
	v_mfma_f32_16x16x32_bf16 v[160:163], v[110:113], v[184:187], v[14:17]
	v_mfma_f32_16x16x32_bf16 v[164:167], v[208:211], v[184:187], v[10:13]
	s_barrier
	s_setprio 0
	s_nop 0
	ds_read_b128 v[10:13], v145
	ds_read_b128 v[14:17], v145 offset:1024
	ds_read_b128 v[180:183], v145 offset:2048
	ds_read_b128 v[144:147], v145 offset:3072
	ds_read_b128 v[26:29], v141 offset:32768
	ds_read_b128 v[30:33], v141 offset:33792
	ds_read_b128 v[42:45], v139 offset:32768
	ds_read_b128 v[46:49], v139 offset:33792
	ds_read_b128 v[184:187], v137 offset:32768
	ds_read_b128 v[188:191], v137 offset:33792
	ds_read_b128 v[196:199], v135 offset:32768
	ds_read_b128 v[204:207], v135 offset:33792
	s_waitcnt vmcnt(2)
	s_setprio 1
	s_barrier
	s_waitcnt lgkmcnt(0)
	v_mfma_f32_16x16x32_bf16 v[74:77], v[10:13], v[26:29], v[126:129]
	v_mfma_f32_16x16x32_bf16 v[126:129], v[14:17], v[30:33], v[74:77]
	v_mfma_f32_16x16x32_bf16 v[74:77], v[180:183], v[26:29], v[122:125]
	v_mfma_f32_16x16x32_bf16 v[122:125], v[144:147], v[30:33], v[74:77]
	v_mfma_f32_16x16x32_bf16 v[74:77], v[10:13], v[42:45], v[118:121]
	v_mfma_f32_16x16x32_bf16 v[110:113], v[14:17], v[46:49], v[74:77]
	v_mfma_f32_16x16x32_bf16 v[74:77], v[180:183], v[42:45], v[114:117]
	v_mfma_f32_16x16x32_bf16 v[106:109], v[144:147], v[46:49], v[74:77]
	v_mfma_f32_16x16x32_bf16 v[74:77], v[10:13], v[184:187], v[130:133]
	v_mfma_f32_16x16x32_bf16 v[94:97], v[14:17], v[188:191], v[74:77]
	v_mfma_f32_16x16x32_bf16 v[74:77], v[180:183], v[184:187], v[148:151]
	v_mfma_f32_16x16x32_bf16 v[90:93], v[144:147], v[188:191], v[74:77]
	v_mfma_f32_16x16x32_bf16 v[74:77], v[10:13], v[196:199], v[102:105]
	v_mfma_f32_16x16x32_bf16 v[78:81], v[14:17], v[204:207], v[74:77]
	v_mfma_f32_16x16x32_bf16 v[74:77], v[180:183], v[196:199], v[98:101]
	v_mfma_f32_16x16x32_bf16 v[74:77], v[144:147], v[204:207], v[74:77]
	s_barrier
;   #define LDA(dst,b,h) for(int m=0;m<4;++m)for(int k=0;k<2;++k) \
;     dst[m][k]=*reinterpret_cast<const bf16x8*>((char*)SA(b,h)+lds_byte(wr*64+m*16+fr,k*32+fq*8))
;   #define LDB(dst,b,h) for(int n=0;n<2;++n)for(int k=0;k<2;++k) \
;     dst[n][k]=*reinterpret_cast<const bf16x8*>((char*)SB(b,h)+lds_byte(wc*32+n*16+fr,k*32+fq*8))
;   #define MMA(ai,bj,At,Bt_) do{__builtin_amdgcn_s_setprio(1); \
;     for(int m=0;m<4;++m)for(int n=0;n<2;++n)for(int k=0;k<2;++k) \
;       acc[ai][bj][m][n]=__builtin_amdgcn_mfma_f32_16x16x32_bf16(Bt_[n][k],At[m][k],acc[ai][bj][m][n],0,0,0); \
;     __builtin_amdgcn_s_setprio(0);}while(0)
;   #define WAIT_V(n) asm volatile("s_waitcnt vmcnt(" #n ")":::"memory")
;   #define WAIT_L(n) asm volatile("s_waitcnt lgkmcnt(" #n ")":::"memory")
;   #define BAR __builtin_amdgcn_s_barrier()
; template <bool TWO, class MID> ...
;     ...
;     LDB(B1,1,1); WAIT_V(0); BAR; WAIT_L(0); MMA(0,1,At,B1); BAR;
;     LDA(At,1,1); BAR; WAIT_L(0); MMA(1,0,At,B0); MMA(1,1,At,B1); BAR; }
;   if(wr==0)BAR;
	s_setprio 0
	ds_read_b128 v[130:133], v143
	ds_read_b128 v[148:151], v143 offset:1024
	ds_read_b128 v[208:211], v143 offset:2048
	ds_read_b128 v[220:223], v143 offset:3072
	s_waitcnt vmcnt(0)
	s_setprio 1
	s_barrier
	s_waitcnt lgkmcnt(0)
	v_mfma_f32_16x16x32_bf16 v[98:101], v[130:133], v[26:29], v[212:215]
	v_mfma_f32_16x16x32_bf16 v[26:29], v[208:211], v[26:29], v[168:171]
	v_mfma_f32_16x16x32_bf16 v[114:117], v[220:223], v[30:33], v[26:29]
	v_mfma_f32_16x16x32_bf16 v[26:29], v[130:133], v[42:45], v[86:89]
	v_mfma_f32_16x16x32_bf16 v[102:105], v[148:151], v[46:49], v[26:29]
	v_mfma_f32_16x16x32_bf16 v[26:29], v[208:211], v[42:45], v[82:85]
	v_mfma_f32_16x16x32_bf16 v[118:121], v[148:151], v[30:33], v[98:101]
	v_mfma_f32_16x16x32_bf16 v[98:101], v[220:223], v[46:49], v[26:29]
	v_mfma_f32_16x16x32_bf16 v[26:29], v[130:133], v[184:187], v[172:175]
	v_mfma_f32_16x16x32_bf16 v[86:89], v[148:151], v[188:191], v[26:29]
	v_mfma_f32_16x16x32_bf16 v[26:29], v[208:211], v[184:187], v[176:179]
	v_mfma_f32_16x16x32_bf16 v[82:85], v[220:223], v[188:191], v[26:29]
	v_mfma_f32_16x16x32_bf16 v[26:29], v[130:133], v[196:199], v[70:73]
	v_mfma_f32_16x16x32_bf16 v[70:73], v[148:151], v[204:207], v[26:29]
	v_mfma_f32_16x16x32_bf16 v[26:29], v[208:211], v[196:199], v[66:69]
	v_mfma_f32_16x16x32_bf16 v[66:69], v[220:223], v[204:207], v[26:29]
	s_barrier
	s_setprio 0
	ds_read_b128 v[168:171], v141 offset:49152
	ds_read_b128 v[140:143], v141 offset:50176
	ds_read_b128 v[172:175], v139 offset:49152
	ds_read_b128 v[176:179], v139 offset:50176
	ds_read_b128 v[184:187], v137 offset:49152
	ds_read_b128 v[136:139], v137 offset:50176
	ds_read_b128 v[188:191], v135 offset:49152
	ds_read_b128 v[196:199], v135 offset:50176
	s_setprio 1
	s_barrier
	s_waitcnt lgkmcnt(0)
	v_mfma_f32_16x16x32_bf16 v[26:29], v[10:13], v[168:171], v[62:65]
	v_mfma_f32_16x16x32_bf16 v[62:65], v[14:17], v[140:143], v[26:29]
	v_mfma_f32_16x16x32_bf16 v[26:29], v[180:183], v[168:171], v[58:61]
	v_mfma_f32_16x16x32_bf16 v[58:61], v[144:147], v[140:143], v[26:29]
	v_mfma_f32_16x16x32_bf16 v[26:29], v[10:13], v[172:175], v[54:57]
	v_mfma_f32_16x16x32_bf16 v[46:49], v[14:17], v[176:179], v[26:29]
	v_mfma_f32_16x16x32_bf16 v[26:29], v[180:183], v[172:175], v[50:53]
	v_mfma_f32_16x16x32_bf16 v[42:45], v[144:147], v[176:179], v[26:29]
	v_mfma_f32_16x16x32_bf16 v[26:29], v[10:13], v[184:187], v[200:203]
	v_mfma_f32_16x16x32_bf16 v[10:13], v[10:13], v[188:191], v[38:41]
	v_mfma_f32_16x16x32_bf16 v[30:33], v[14:17], v[136:139], v[26:29]
	v_mfma_f32_16x16x32_bf16 v[26:29], v[180:183], v[184:187], v[216:219]
	v_mfma_f32_16x16x32_bf16 v[14:17], v[14:17], v[196:199], v[10:13]
	v_mfma_f32_16x16x32_bf16 v[10:13], v[180:183], v[188:191], v[34:37]
	v_mfma_f32_16x16x32_bf16 v[26:29], v[144:147], v[136:139], v[26:29]
	v_mfma_f32_16x16x32_bf16 v[10:13], v[144:147], v[196:199], v[10:13]
	s_setprio 0
	s_setprio 1
	v_mfma_f32_16x16x32_bf16 v[34:37], v[130:133], v[168:171], v[152:155]
	v_mfma_f32_16x16x32_bf16 v[54:57], v[148:151], v[140:143], v[34:37]
	v_mfma_f32_16x16x32_bf16 v[34:37], v[208:211], v[168:171], v[156:159]
	v_mfma_f32_16x16x32_bf16 v[18:21], v[208:211], v[172:175], v[18:21]
	v_mfma_f32_16x16x32_bf16 v[50:53], v[220:223], v[140:143], v[34:37]
	v_mfma_f32_16x16x32_bf16 v[22:25], v[130:133], v[172:175], v[22:25]
	v_mfma_f32_16x16x32_bf16 v[34:37], v[220:223], v[176:179], v[18:21]
	v_mfma_f32_16x16x32_bf16 v[18:21], v[130:133], v[184:187], v[160:163]
	v_mfma_f32_16x16x32_bf16 v[38:41], v[148:151], v[176:179], v[22:25]
	v_mfma_f32_16x16x32_bf16 v[22:25], v[148:151], v[136:139], v[18:21]
	v_mfma_f32_16x16x32_bf16 v[18:21], v[208:211], v[184:187], v[164:167]
	v_mfma_f32_16x16x32_bf16 v[6:9], v[130:133], v[188:191], v[6:9]
	v_mfma_f32_16x16x32_bf16 v[2:5], v[208:211], v[188:191], v[2:5]
	v_mfma_f32_16x16x32_bf16 v[18:21], v[220:223], v[136:139], v[18:21]
	v_mfma_f32_16x16x32_bf16 v[6:9], v[148:151], v[196:199], v[6:9]
	v_mfma_f32_16x16x32_bf16 v[2:5], v[220:223], v[196:199], v[2:5]
	s_setprio 0
	v_cmp_gt_u32_e32 vcc, s30, v1
	s_barrier
	s_and_saveexec_b64 s[4:5], vcc
	s_cbranch_execz .LBB0_492
	s_barrier

;   #define LDA(dst,b,h) for(int m=0;m<4;++m)for(int k=0;k<2;++k) \
;     dst[m][k]=*reinterpret_cast<const bf16x8*>((char*)SA(b,h)+lds_byte(wr*64+m*16+fr,k*32+fq*8))
;   #define LDB(dst,b,h) for(int n=0;n<2;++n)for(int k=0;k<2;++k) \
;     dst[n][k]=*reinterpret_cast<const bf16x8*>((char*)SB(b,h)+lds_byte(wc*32+n*16+fr,k*32+fq*8))
;   #define MMA(ai,bj,At,Bt_) do{__builtin_amdgcn_s_setprio(1); \
;     for(int m=0;m<4;++m)for(int n=0;n<2;++n)for(int k=0;k<2;++k) \
;       acc[ai][bj][m][n]=__builtin_amdgcn_mfma_f32_16x16x32_bf16(Bt_[n][k],At[m][k],acc[ai][bj][m][n],0,0,0); \
;     __builtin_amdgcn_s_setprio(0);}while(0)
;   #define WAIT_V(n) asm volatile("s_waitcnt vmcnt(" #n ")":::"memory")
;   #define WAIT_L(n) asm volatile("s_waitcnt lgkmcnt(" #n ")":::"memory")
;   #define BAR __builtin_amdgcn_s_barrier()
;   #define SCHED __builtin_amdgcn_sched_barrier(0)
; template <bool TWO, class MID> ...
;     ...
;     LDB(B0,0,0); SCHED; LDA(At,0,0); STAGE_A(SA(1,1),1,t+1);
;     WAIT_L(8); BAR; WAIT_L(0); MMA(0,0,At,B0); BAR; SCHED;
;     LDB(B1,0,1); STAGE_B(SB(0,0),0,t+2);
;     BAR; WAIT_L(0); MMA(0,1,At,B1); BAR;
;     LDA(At,0,1); STAGE_A(SA(0,0),0,t+2);
;     BAR; WAIT_L(0); MMA(1,0,At,B0); BAR; SCHED;
;     STAGE_B(SB(0,1),1,t+2);
;     WAIT_V(6); BAR; MMA(1,1,At,B1); BAR;
.LBB0_562:
	ds_read_b128 v[166:169], v149
	ds_read_b128 v[170:173], v149 offset:1024
	ds_read_b128 v[174:177], v149 offset:2048
	ds_read_b128 v[178:181], v149 offset:3072
	ds_read_b128 v[182:185], v141
	ds_read_b128 v[186:189], v141 offset:1024
	ds_read_b128 v[190:193], v139
	ds_read_b128 v[196:199], v139 offset:1024
	ds_read_b128 v[200:203], v137
	ds_read_b128 v[204:207], v137 offset:1024
	ds_read_b128 v[208:211], v135
	ds_read_b128 v[212:215], v135 offset:1024
	s_add_u32 s23, s4, s12
	s_addc_u32 s24, s5, s13
	s_add_u32 m0, s98, 0xc000
	s_add_u32 s26, s23, 0x8080080
	s_addc_u32 s27, s24, 0
	global_load_lds_dwordx4 v132, s[26:27]
	s_add_u32 m0, s98, 0xe000
	s_setprio 1
	global_load_lds_dwordx4 v130, s[26:27]
	s_waitcnt lgkmcnt(8)
	s_barrier
	s_waitcnt lgkmcnt(0)
	v_mfma_f32_16x16x32_bf16 v[126:129], v[166:169], v[182:185], v[126:129]
	v_mfma_f32_16x16x32_bf16 v[122:125], v[174:177], v[182:185], v[122:125]
	v_mfma_f32_16x16x32_bf16 v[118:121], v[166:169], v[190:193], v[118:121]
	v_mfma_f32_16x16x32_bf16 v[114:117], v[174:177], v[190:193], v[114:117]
	v_mfma_f32_16x16x32_bf16 v[110:113], v[166:169], v[200:203], v[110:113]
	v_mfma_f32_16x16x32_bf16 v[106:109], v[174:177], v[200:203], v[106:109]
	v_mfma_f32_16x16x32_bf16 v[102:105], v[166:169], v[208:211], v[102:105]
	v_mfma_f32_16x16x32_bf16 v[98:101], v[174:177], v[208:211], v[98:101]
	v_mfma_f32_16x16x32_bf16 v[126:129], v[170:173], v[186:189], v[126:129]
	v_mfma_f32_16x16x32_bf16 v[122:125], v[178:181], v[186:189], v[122:125]
	v_mfma_f32_16x16x32_bf16 v[118:121], v[170:173], v[196:199], v[118:121]
	v_mfma_f32_16x16x32_bf16 v[114:117], v[178:181], v[196:199], v[114:117]
	v_mfma_f32_16x16x32_bf16 v[110:113], v[170:173], v[204:207], v[110:113]
	v_mfma_f32_16x16x32_bf16 v[106:109], v[178:181], v[204:207], v[106:109]
	v_mfma_f32_16x16x32_bf16 v[102:105], v[170:173], v[212:215], v[102:105]
	v_mfma_f32_16x16x32_bf16 v[98:101], v[178:181], v[212:215], v[98:101]
	s_barrier
	s_setprio 0
	s_add_u32 s25, s4, s14
	ds_read_b128 v[216:219], v147
	ds_read_b128 v[220:223], v147 offset:1024
	ds_read_b128 v[224:227], v147 offset:2048
	ds_read_b128 v[228:231], v147 offset:3072
	s_addc_u32 s26, s5, s15
	s_add_u32 m0, s98, 0x10000
	s_add_u32 s28, s25, 0x3c00100
	s_addc_u32 s29, s26, 0
	global_load_lds_dwordx4 v132, s[28:29]
	s_add_u32 m0, s98, 0x12000
	s_setprio 1
	global_load_lds_dwordx4 v130, s[28:29]
	s_barrier
	s_waitcnt lgkmcnt(0)
	v_mfma_f32_16x16x32_bf16 v[94:97], v[216:219], v[182:185], v[94:97]
	v_mfma_f32_16x16x32_bf16 v[90:93], v[224:227], v[182:185], v[90:93]
	v_mfma_f32_16x16x32_bf16 v[86:89], v[216:219], v[190:193], v[86:89]
	v_mfma_f32_16x16x32_bf16 v[82:85], v[224:227], v[190:193], v[82:85]
	v_mfma_f32_16x16x32_bf16 v[78:81], v[216:219], v[200:203], v[78:81]
	v_mfma_f32_16x16x32_bf16 v[74:77], v[224:227], v[200:203], v[74:77]
	v_mfma_f32_16x16x32_bf16 v[70:73], v[216:219], v[208:211], v[70:73]
	v_mfma_f32_16x16x32_bf16 v[66:69], v[224:227], v[208:211], v[66:69]
	v_mfma_f32_16x16x32_bf16 v[94:97], v[220:223], v[186:189], v[94:97]
	v_mfma_f32_16x16x32_bf16 v[90:93], v[228:231], v[186:189], v[90:93]
	v_mfma_f32_16x16x32_bf16 v[86:89], v[220:223], v[196:199], v[86:89]
	v_mfma_f32_16x16x32_bf16 v[82:85], v[228:231], v[196:199], v[82:85]
	v_mfma_f32_16x16x32_bf16 v[78:81], v[220:223], v[204:207], v[78:81]
	v_mfma_f32_16x16x32_bf16 v[74:77], v[228:231], v[204:207], v[74:77]
	v_mfma_f32_16x16x32_bf16 v[70:73], v[220:223], v[212:215], v[70:73]
	v_mfma_f32_16x16x32_bf16 v[66:69], v[228:231], v[212:215], v[66:69]
	s_barrier
	s_setprio 0
	ds_read_b128 v[182:185], v141 offset:16384
	ds_read_b128 v[186:189], v141 offset:17408
	ds_read_b128 v[190:193], v139 offset:16384
	ds_read_b128 v[196:199], v139 offset:17408
	ds_read_b128 v[200:203], v137 offset:16384
	ds_read_b128 v[204:207], v137 offset:17408
	ds_read_b128 v[208:211], v135 offset:16384
	ds_read_b128 v[212:215], v135 offset:17408
	s_add_u32 m0, s98, 0x0
	s_add_u32 s28, s23, 0x8000100
	s_addc_u32 s29, s24, 0
	global_load_lds_dwordx4 v132, s[28:29]
	s_add_u32 m0, s98, 0x2000
	s_setprio 1
	global_load_lds_dwordx4 v130, s[28:29]
	s_barrier
	s_waitcnt lgkmcnt(0)
	v_mfma_f32_16x16x32_bf16 v[62:65], v[166:169], v[182:185], v[62:65]
	v_mfma_f32_16x16x32_bf16 v[58:61], v[174:177], v[182:185], v[58:61]
	v_mfma_f32_16x16x32_bf16 v[54:57], v[166:169], v[190:193], v[54:57]
	v_mfma_f32_16x16x32_bf16 v[50:53], v[174:177], v[190:193], v[50:53]
	v_mfma_f32_16x16x32_bf16 v[46:49], v[166:169], v[200:203], v[46:49]
	v_mfma_f32_16x16x32_bf16 v[42:45], v[174:177], v[200:203], v[42:45]
	v_mfma_f32_16x16x32_bf16 v[38:41], v[166:169], v[208:211], v[38:41]
	v_mfma_f32_16x16x32_bf16 v[34:37], v[174:177], v[208:211], v[34:37]
	v_mfma_f32_16x16x32_bf16 v[62:65], v[170:173], v[186:189], v[62:65]
	v_mfma_f32_16x16x32_bf16 v[58:61], v[178:181], v[186:189], v[58:61]
	v_mfma_f32_16x16x32_bf16 v[54:57], v[170:173], v[196:199], v[54:57]
	v_mfma_f32_16x16x32_bf16 v[50:53], v[178:181], v[196:199], v[50:53]
	v_mfma_f32_16x16x32_bf16 v[46:49], v[170:173], v[204:207], v[46:49]
	v_mfma_f32_16x16x32_bf16 v[42:45], v[178:181], v[204:207], v[42:45]
	v_mfma_f32_16x16x32_bf16 v[38:41], v[170:173], v[212:215], v[38:41]
	v_mfma_f32_16x16x32_bf16 v[34:37], v[178:181], v[212:215], v[34:37]
	s_barrier
	s_setprio 0
	s_add_u32 m0, s98, 0x14000
	s_add_u32 s28, s25, 0x3c80100
	s_addc_u32 s29, s26, 0
	global_load_lds_dwordx4 v132, s[28:29]
	s_add_u32 m0, s98, 0x16000
	s_setprio 1
	global_load_lds_dwordx4 v130, s[28:29]
	s_waitcnt vmcnt(6)
	s_barrier
;   #define LDA(dst,b,h) for(int m=0;m<4;++m)for(int k=0;k<2;++k) \
;     dst[m][k]=*reinterpret_cast<const bf16x8*>((char*)SA(b,h)+lds_byte(wr*64+m*16+fr,k*32+fq*8))
;   #define LDB(dst,b,h) for(int n=0;n<2;++n)for(int k=0;k<2;++k) \
;     dst[n][k]=*reinterpret_cast<const bf16x8*>((char*)SB(b,h)+lds_byte(wc*32+n*16+fr,k*32+fq*8))
;   #define MMA(ai,bj,At,Bt_) do{__builtin_amdgcn_s_setprio(1); \
;     for(int m=0;m<4;++m)for(int n=0;n<2;++n)for(int k=0;k<2;++k) \
;       acc[ai][bj][m][n]=__builtin_amdgcn_mfma_f32_16x16x32_bf16(Bt_[n][k],At[m][k],acc[ai][bj][m][n],0,0,0); \
;     __builtin_amdgcn_s_setprio(0);}while(0)
;   #define WAIT_V(n) asm volatile("s_waitcnt vmcnt(" #n ")":::"memory")
;   #define WAIT_L(n) asm volatile("s_waitcnt lgkmcnt(" #n ")":::"memory")
;   #define BAR __builtin_amdgcn_s_barrier()
;   #define SCHED __builtin_amdgcn_sched_barrier(0)
; template <bool TWO, class MID> ...
;     ...
;     WAIT_V(6); BAR; MMA(1,1,At,B1); BAR;
;     LDB(B0,1,0); SCHED; LDA(At,1,0); STAGE_A(SA(0,1),1,t+2);
;     WAIT_L(8); BAR; WAIT_L(0); MMA(0,0,At,B0); BAR; SCHED;
;     LDB(B1,1,1); STAGE_B(SB(1,0),0,t+3);
;     BAR; WAIT_L(0); MMA(0,1,At,B1); BAR;
;     LDA(At,1,1); STAGE_A(SA(1,0),0,t+3);
	v_mfma_f32_16x16x32_bf16 v[30:33], v[216:219], v[182:185], v[30:33]
	v_mfma_f32_16x16x32_bf16 v[26:29], v[224:227], v[182:185], v[26:29]
	v_mfma_f32_16x16x32_bf16 v[22:25], v[216:219], v[190:193], v[22:25]
	v_mfma_f32_16x16x32_bf16 v[18:21], v[224:227], v[190:193], v[18:21]
	v_mfma_f32_16x16x32_bf16 v[14:17], v[216:219], v[200:203], v[14:17]
	v_mfma_f32_16x16x32_bf16 v[10:13], v[224:227], v[200:203], v[10:13]
	v_mfma_f32_16x16x32_bf16 v[6:9], v[216:219], v[208:211], v[6:9]
	v_mfma_f32_16x16x32_bf16 v[2:5], v[224:227], v[208:211], v[2:5]
	v_mfma_f32_16x16x32_bf16 v[30:33], v[220:223], v[186:189], v[30:33]
	v_mfma_f32_16x16x32_bf16 v[26:29], v[228:231], v[186:189], v[26:29]
	v_mfma_f32_16x16x32_bf16 v[22:25], v[220:223], v[196:199], v[22:25]
	v_mfma_f32_16x16x32_bf16 v[18:21], v[228:231], v[196:199], v[18:21]
	v_mfma_f32_16x16x32_bf16 v[14:17], v[220:223], v[204:207], v[14:17]
	v_mfma_f32_16x16x32_bf16 v[10:13], v[228:231], v[204:207], v[10:13]
	v_mfma_f32_16x16x32_bf16 v[6:9], v[220:223], v[212:215], v[6:9]
	v_mfma_f32_16x16x32_bf16 v[2:5], v[228:231], v[212:215], v[2:5]
	s_barrier
	s_setprio 0
	ds_read_b128 v[166:169], v145
	ds_read_b128 v[170:173], v145 offset:1024
	ds_read_b128 v[174:177], v145 offset:2048
	ds_read_b128 v[178:181], v145 offset:3072
	ds_read_b128 v[182:185], v141 offset:32768
	ds_read_b128 v[186:189], v141 offset:33792
	ds_read_b128 v[190:193], v139 offset:32768
	ds_read_b128 v[196:199], v139 offset:33792
	ds_read_b128 v[200:203], v137 offset:32768
	ds_read_b128 v[204:207], v137 offset:33792
	ds_read_b128 v[208:211], v135 offset:32768
	ds_read_b128 v[212:215], v135 offset:33792
	s_add_u32 m0, s98, 0x4000
	s_add_u32 s28, s23, 0x8080100
	s_addc_u32 s29, s24, 0
	global_load_lds_dwordx4 v132, s[28:29]
	s_add_u32 m0, s98, 0x6000
	s_setprio 1
	global_load_lds_dwordx4 v130, s[28:29]
	s_waitcnt lgkmcnt(8)
	s_barrier
	s_waitcnt lgkmcnt(0)
	v_mfma_f32_16x16x32_bf16 v[126:129], v[166:169], v[182:185], v[126:129]
	v_mfma_f32_16x16x32_bf16 v[122:125], v[174:177], v[182:185], v[122:125]
	v_mfma_f32_16x16x32_bf16 v[118:121], v[166:169], v[190:193], v[118:121]
	v_mfma_f32_16x16x32_bf16 v[114:117], v[174:177], v[190:193], v[114:117]
	v_mfma_f32_16x16x32_bf16 v[110:113], v[166:169], v[200:203], v[110:113]
	v_mfma_f32_16x16x32_bf16 v[106:109], v[174:177], v[200:203], v[106:109]
	v_mfma_f32_16x16x32_bf16 v[102:105], v[166:169], v[208:211], v[102:105]
	v_mfma_f32_16x16x32_bf16 v[98:101], v[174:177], v[208:211], v[98:101]
	v_mfma_f32_16x16x32_bf16 v[126:129], v[170:173], v[186:189], v[126:129]
	v_mfma_f32_16x16x32_bf16 v[122:125], v[178:181], v[186:189], v[122:125]
	v_mfma_f32_16x16x32_bf16 v[118:121], v[170:173], v[196:199], v[118:121]
	v_mfma_f32_16x16x32_bf16 v[114:117], v[178:181], v[196:199], v[114:117]
	v_mfma_f32_16x16x32_bf16 v[110:113], v[170:173], v[204:207], v[110:113]
	v_mfma_f32_16x16x32_bf16 v[106:109], v[178:181], v[204:207], v[106:109]
	v_mfma_f32_16x16x32_bf16 v[102:105], v[170:173], v[212:215], v[102:105]
	v_mfma_f32_16x16x32_bf16 v[98:101], v[178:181], v[212:215], v[98:101]
	s_barrier
	s_setprio 0
	ds_read_b128 v[216:219], v143
	ds_read_b128 v[220:223], v143 offset:1024
	ds_read_b128 v[224:227], v143 offset:2048
	ds_read_b128 v[228:231], v143 offset:3072
	s_add_u32 m0, s98, 0x18000
	s_add_u32 s28, s25, 0x3c00180
	s_addc_u32 s29, s26, 0
	global_load_lds_dwordx4 v132, s[28:29]
	s_add_u32 m0, s98, 0x1a000
	s_setprio 1
	global_load_lds_dwordx4 v130, s[28:29]
	s_barrier
	s_waitcnt lgkmcnt(0)
	v_mfma_f32_16x16x32_bf16 v[94:97], v[216:219], v[182:185], v[94:97]
	v_mfma_f32_16x16x32_bf16 v[90:93], v[224:227], v[182:185], v[90:93]
	v_mfma_f32_16x16x32_bf16 v[86:89], v[216:219], v[190:193], v[86:89]
	v_mfma_f32_16x16x32_bf16 v[82:85], v[224:227], v[190:193], v[82:85]
	v_mfma_f32_16x16x32_bf16 v[78:81], v[216:219], v[200:203], v[78:81]
	v_mfma_f32_16x16x32_bf16 v[74:77], v[224:227], v[200:203], v[74:77]
	v_mfma_f32_16x16x32_bf16 v[70:73], v[216:219], v[208:211], v[70:73]
	v_mfma_f32_16x16x32_bf16 v[66:69], v[224:227], v[208:211], v[66:69]
	v_mfma_f32_16x16x32_bf16 v[94:97], v[220:223], v[186:189], v[94:97]
	v_mfma_f32_16x16x32_bf16 v[90:93], v[228:231], v[186:189], v[90:93]
	v_mfma_f32_16x16x32_bf16 v[86:89], v[220:223], v[196:199], v[86:89]
	v_mfma_f32_16x16x32_bf16 v[82:85], v[228:231], v[196:199], v[82:85]
	v_mfma_f32_16x16x32_bf16 v[78:81], v[220:223], v[204:207], v[78:81]
	v_mfma_f32_16x16x32_bf16 v[74:77], v[228:231], v[204:207], v[74:77]
	v_mfma_f32_16x16x32_bf16 v[70:73], v[220:223], v[212:215], v[70:73]
	v_mfma_f32_16x16x32_bf16 v[66:69], v[228:231], v[212:215], v[66:69]
	s_barrier
	s_setprio 0
	ds_read_b128 v[182:185], v141 offset:49152
	ds_read_b128 v[186:189], v141 offset:50176
	ds_read_b128 v[190:193], v139 offset:49152
	ds_read_b128 v[196:199], v139 offset:50176
	ds_read_b128 v[200:203], v137 offset:49152
	ds_read_b128 v[204:207], v137 offset:50176
	ds_read_b128 v[208:211], v135 offset:49152
	ds_read_b128 v[212:215], v135 offset:50176
	s_add_u32 m0, s98, 0x8000
	s_add_u32 s28, s23, 0x8000180
	s_addc_u32 s29, s24, 0
	global_load_lds_dwordx4 v132, s[28:29]
	s_add_u32 m0, s98, 0xa000
	s_setprio 1
	global_load_lds_dwordx4 v130, s[28:29]
	s_barrier
;   #define LDA(dst,b,h) for(int m=0;m<4;++m)for(int k=0;k<2;++k) \
;     dst[m][k]=*reinterpret_cast<const bf16x8*>((char*)SA(b,h)+lds_byte(wr*64+m*16+fr,k*32+fq*8))
;   #define LDB(dst,b,h) for(int n=0;n<2;++n)for(int k=0;k<2;++k) \
;     dst[n][k]=*reinterpret_cast<const bf16x8*>((char*)SB(b,h)+lds_byte(wc*32+n*16+fr,k*32+fq*8))
;   #define MMA(ai,bj,At,Bt_) do{__builtin_amdgcn_s_setprio(1); \
;     for(int m=0;m<4;++m)for(int n=0;n<2;++n)for(int k=0;k<2;++k) \
;       acc[ai][bj][m][n]=__builtin_amdgcn_mfma_f32_16x16x32_bf16(Bt_[n][k],At[m][k],acc[ai][bj][m][n],0,0,0); \
;     __builtin_amdgcn_s_setprio(0);}while(0)
;   #define WAIT_V(n) asm volatile("s_waitcnt vmcnt(" #n ")":::"memory")
;   #define WAIT_L(n) asm volatile("s_waitcnt lgkmcnt(" #n ")":::"memory")
;   #define BAR __builtin_amdgcn_s_barrier()
;   #define SCHED __builtin_amdgcn_sched_barrier(0)
; template <bool TWO, class MID> ...
;     ...
;     BAR; WAIT_L(0); MMA(1,0,At,B0); BAR; SCHED;
;     STAGE_B(SB(1,1),1,t+3);
;     WAIT_V(6); BAR; MMA(1,1,At,B1); BAR;
;   }
;   { LDB(B0,0,0); LDA(At,0,0); STAGE_A(SA(1,1),1,nt-1);
;     BAR; WAIT_L(0); MMA(0,0,At,B0); BAR;
;     LDB(B1,0,1); BAR; WAIT_L(0); MMA(0,1,At,B1); BAR;
	s_waitcnt lgkmcnt(0)
	v_mfma_f32_16x16x32_bf16 v[62:65], v[166:169], v[182:185], v[62:65]
	v_mfma_f32_16x16x32_bf16 v[58:61], v[174:177], v[182:185], v[58:61]
	v_mfma_f32_16x16x32_bf16 v[54:57], v[166:169], v[190:193], v[54:57]
	v_mfma_f32_16x16x32_bf16 v[50:53], v[174:177], v[190:193], v[50:53]
	v_mfma_f32_16x16x32_bf16 v[46:49], v[166:169], v[200:203], v[46:49]
	v_mfma_f32_16x16x32_bf16 v[42:45], v[174:177], v[200:203], v[42:45]
	v_mfma_f32_16x16x32_bf16 v[38:41], v[166:169], v[208:211], v[38:41]
	v_mfma_f32_16x16x32_bf16 v[34:37], v[174:177], v[208:211], v[34:37]
	v_mfma_f32_16x16x32_bf16 v[62:65], v[170:173], v[186:189], v[62:65]
	v_mfma_f32_16x16x32_bf16 v[58:61], v[178:181], v[186:189], v[58:61]
	v_mfma_f32_16x16x32_bf16 v[54:57], v[170:173], v[196:199], v[54:57]
	v_mfma_f32_16x16x32_bf16 v[50:53], v[178:181], v[196:199], v[50:53]
	v_mfma_f32_16x16x32_bf16 v[46:49], v[170:173], v[204:207], v[46:49]
	v_mfma_f32_16x16x32_bf16 v[42:45], v[178:181], v[204:207], v[42:45]
	v_mfma_f32_16x16x32_bf16 v[38:41], v[170:173], v[212:215], v[38:41]
	v_mfma_f32_16x16x32_bf16 v[34:37], v[178:181], v[212:215], v[34:37]
	s_barrier
	s_setprio 0
	s_add_u32 m0, s98, 0x1c000
	s_add_u32 s24, s25, 0x3c80180
	s_addc_u32 s25, s26, 0
	global_load_lds_dwordx4 v132, s[24:25]
	s_add_u32 m0, s98, 0x1e000
	s_setprio 1
	global_load_lds_dwordx4 v130, s[24:25]
	s_waitcnt vmcnt(6)
	s_barrier
	v_mfma_f32_16x16x32_bf16 v[30:33], v[216:219], v[182:185], v[30:33]
	v_mfma_f32_16x16x32_bf16 v[26:29], v[224:227], v[182:185], v[26:29]
	v_mfma_f32_16x16x32_bf16 v[22:25], v[216:219], v[190:193], v[22:25]
	v_mfma_f32_16x16x32_bf16 v[18:21], v[224:227], v[190:193], v[18:21]
	v_mfma_f32_16x16x32_bf16 v[14:17], v[216:219], v[200:203], v[14:17]
	v_mfma_f32_16x16x32_bf16 v[10:13], v[224:227], v[200:203], v[10:13]
	v_mfma_f32_16x16x32_bf16 v[6:9], v[216:219], v[208:211], v[6:9]
	v_mfma_f32_16x16x32_bf16 v[2:5], v[224:227], v[208:211], v[2:5]
	v_mfma_f32_16x16x32_bf16 v[30:33], v[220:223], v[186:189], v[30:33]
	v_mfma_f32_16x16x32_bf16 v[26:29], v[228:231], v[186:189], v[26:29]
	v_mfma_f32_16x16x32_bf16 v[22:25], v[220:223], v[196:199], v[22:25]
	v_mfma_f32_16x16x32_bf16 v[18:21], v[228:231], v[196:199], v[18:21]
	v_mfma_f32_16x16x32_bf16 v[14:17], v[220:223], v[204:207], v[14:17]
	v_mfma_f32_16x16x32_bf16 v[10:13], v[228:231], v[204:207], v[10:13]
	v_mfma_f32_16x16x32_bf16 v[6:9], v[220:223], v[212:215], v[6:9]
	v_mfma_f32_16x16x32_bf16 v[2:5], v[228:231], v[212:215], v[2:5]
	s_barrier
	s_setprio 0
	s_add_i32 s22, s22, 2
	s_add_u32 s4, s4, 0x100
	s_addc_u32 s5, s5, 0
	s_cmp_lt_u32 s22, 28
	s_cbranch_scc1 .LBB0_562
	ds_read_b128 v[152:155], v149
	ds_read_b128 v[156:159], v149 offset:1024
	ds_read_b128 v[160:163], v149 offset:2048
	ds_read_b128 v[164:167], v149 offset:3072
	ds_read_b128 v[168:171], v141
	ds_read_b128 v[172:175], v141 offset:1024
	ds_read_b128 v[176:179], v139
	ds_read_b128 v[180:183], v139 offset:1024
	ds_read_b128 v[184:187], v137
	ds_read_b128 v[188:191], v137 offset:1024
	ds_read_b128 v[196:199], v135
	ds_read_b128 v[200:203], v135 offset:1024
	s_add_u32 s4, s19, 0x80f80
	s_addc_u32 s5, s21, 0
	v_lshl_add_u64 v[132:133], s[4:5], 0, v[132:133]
	v_readfirstlane_b32 s12, v148
	s_mov_b32 m0, s12
	global_load_lds_dwordx4 v[132:133], off
	v_lshl_add_u64 v[130:131], s[4:5], 0, v[130:131]
	v_readfirstlane_b32 s4, v150
	s_mov_b32 m0, s4
	global_load_lds_dwordx4 v[130:131], off
	s_setprio 1
	s_barrier
	s_waitcnt lgkmcnt(0)
	v_mfma_f32_16x16x32_bf16 v[126:129], v[152:155], v[168:171], v[126:129]
	v_mfma_f32_16x16x32_bf16 v[122:125], v[160:163], v[168:171], v[122:125]
	v_mfma_f32_16x16x32_bf16 v[114:117], v[160:163], v[176:179], v[114:117]
	v_mfma_f32_16x16x32_bf16 v[106:109], v[160:163], v[184:187], v[106:109]
	v_mfma_f32_16x16x32_bf16 v[98:101], v[160:163], v[196:199], v[98:101]
	v_mfma_f32_16x16x32_bf16 v[126:129], v[156:159], v[172:175], v[126:129]
	v_mfma_f32_16x16x32_bf16 v[122:125], v[164:167], v[172:175], v[122:125]
	v_mfma_f32_16x16x32_bf16 v[118:121], v[152:155], v[176:179], v[118:121]
	v_mfma_f32_16x16x32_bf16 v[114:117], v[164:167], v[180:183], v[114:117]
	v_mfma_f32_16x16x32_bf16 v[110:113], v[152:155], v[184:187], v[110:113]
	v_mfma_f32_16x16x32_bf16 v[106:109], v[164:167], v[188:191], v[106:109]
	v_mfma_f32_16x16x32_bf16 v[102:105], v[152:155], v[196:199], v[102:105]
	v_mfma_f32_16x16x32_bf16 v[98:101], v[164:167], v[200:203], v[98:101]
	v_mfma_f32_16x16x32_bf16 v[130:133], v[156:159], v[180:183], v[118:121]
	v_mfma_f32_16x16x32_bf16 v[148:151], v[156:159], v[188:191], v[110:113]
	v_mfma_f32_16x16x32_bf16 v[204:207], v[156:159], v[200:203], v[102:105]
	s_barrier
	s_setprio 0
	s_nop 0
	ds_read_b128 v[102:105], v147
	ds_read_b128 v[110:113], v147 offset:1024
	ds_read_b128 v[118:121], v147 offset:2048
	ds_read_b128 v[208:211], v147 offset:3072
	s_setprio 1
	s_barrier
	s_waitcnt lgkmcnt(0)
	v_mfma_f32_16x16x32_bf16 v[90:93], v[118:121], v[168:171], v[90:93]
	v_mfma_f32_16x16x32_bf16 v[82:85], v[118:121], v[176:179], v[82:85]
	v_mfma_f32_16x16x32_bf16 v[74:77], v[118:121], v[184:187], v[74:77]
	v_mfma_f32_16x16x32_bf16 v[66:69], v[118:121], v[196:199], v[66:69]
	v_mfma_f32_16x16x32_bf16 v[94:97], v[102:105], v[168:171], v[94:97]
	v_mfma_f32_16x16x32_bf16 v[90:93], v[208:211], v[172:175], v[90:93]
	v_mfma_f32_16x16x32_bf16 v[86:89], v[102:105], v[176:179], v[86:89]
	v_mfma_f32_16x16x32_bf16 v[82:85], v[208:211], v[180:183], v[82:85]
	v_mfma_f32_16x16x32_bf16 v[78:81], v[102:105], v[184:187], v[78:81]
	v_mfma_f32_16x16x32_bf16 v[74:77], v[208:211], v[188:191], v[74:77]
	v_mfma_f32_16x16x32_bf16 v[70:73], v[102:105], v[196:199], v[70:73]
	v_mfma_f32_16x16x32_bf16 v[66:69], v[208:211], v[200:203], v[66:69]
	v_mfma_f32_16x16x32_bf16 v[212:215], v[110:113], v[172:175], v[94:97]
	v_mfma_f32_16x16x32_bf16 v[168:171], v[110:113], v[180:183], v[86:89]
	v_mfma_f32_16x16x32_bf16 v[172:175], v[110:113], v[188:191], v[78:81]
	v_mfma_f32_16x16x32_bf16 v[176:179], v[110:113], v[200:203], v[70:73]
	s_barrier
;   #define LDA(dst,b,h) for(int m=0;m<4;++m)for(int k=0;k<2;++k) \
;     dst[m][k]=*reinterpret_cast<const bf16x8*>((char*)SA(b,h)+lds_byte(wr*64+m*16+fr,k*32+fq*8))
;   #define LDB(dst,b,h) for(int n=0;n<2;++n)for(int k=0;k<2;++k) \
;     dst[n][k]=*reinterpret_cast<const bf16x8*>((char*)SB(b,h)+lds_byte(wc*32+n*16+fr,k*32+fq*8))
;   #define MMA(ai,bj,At,Bt_) do{__builtin_amdgcn_s_setprio(1); \
;     for(int m=0;m<4;++m)for(int n=0;n<2;++n)for(int k=0;k<2;++k) \
;       acc[ai][bj][m][n]=__builtin_amdgcn_mfma_f32_16x16x32_bf16(Bt_[n][k],At[m][k],acc[ai][bj][m][n],0,0,0); \
;     __builtin_amdgcn_s_setprio(0);}while(0)
;   #define WAIT_V(n) asm volatile("s_waitcnt vmcnt(" #n ")":::"memory")
;   #define WAIT_L(n) asm volatile("s_waitcnt lgkmcnt(" #n ")":::"memory")
;   #define BAR __builtin_amdgcn_s_barrier()
; template <bool TWO, class MID> ...
;     ...
;     LDA(At,0,1); WAIT_V(4); BAR; WAIT_L(0); MMA(1,0,At,B0); MMA(1,1,At,B1); BAR; }
;   { LDB(B0,1,0); LDA(At,1,0); WAIT_V(2); BAR; WAIT_L(0); MMA(0,0,At,B0); BAR;
	s_setprio 0
	s_nop 0
	ds_read_b128 v[70:73], v141 offset:16384
	ds_read_b128 v[78:81], v141 offset:17408
	ds_read_b128 v[86:89], v139 offset:16384
	ds_read_b128 v[94:97], v139 offset:17408
	ds_read_b128 v[180:183], v137 offset:16384
	ds_read_b128 v[184:187], v137 offset:17408
	ds_read_b128 v[188:191], v135 offset:16384
	ds_read_b128 v[196:199], v135 offset:17408
	s_waitcnt vmcnt(4)
	s_setprio 1
	s_barrier
	s_waitcnt lgkmcnt(0)
	v_mfma_f32_16x16x32_bf16 v[62:65], v[152:155], v[70:73], v[62:65]
	v_mfma_f32_16x16x32_bf16 v[58:61], v[160:163], v[70:73], v[58:61]
	v_mfma_f32_16x16x32_bf16 v[54:57], v[152:155], v[86:89], v[54:57]
	v_mfma_f32_16x16x32_bf16 v[50:53], v[160:163], v[86:89], v[50:53]
	v_mfma_f32_16x16x32_bf16 v[38:41], v[152:155], v[188:191], v[38:41]
	v_mfma_f32_16x16x32_bf16 v[34:37], v[160:163], v[188:191], v[34:37]
	v_mfma_f32_16x16x32_bf16 v[62:65], v[156:159], v[78:81], v[62:65]
	v_mfma_f32_16x16x32_bf16 v[58:61], v[164:167], v[78:81], v[58:61]
	v_mfma_f32_16x16x32_bf16 v[54:57], v[156:159], v[94:97], v[54:57]
	v_mfma_f32_16x16x32_bf16 v[50:53], v[164:167], v[94:97], v[50:53]
	v_mfma_f32_16x16x32_bf16 v[46:49], v[152:155], v[180:183], v[46:49]
	v_mfma_f32_16x16x32_bf16 v[42:45], v[160:163], v[180:183], v[42:45]
	v_mfma_f32_16x16x32_bf16 v[38:41], v[156:159], v[196:199], v[38:41]
	v_mfma_f32_16x16x32_bf16 v[34:37], v[164:167], v[196:199], v[34:37]
	v_mfma_f32_16x16x32_bf16 v[200:203], v[156:159], v[184:187], v[46:49]
	v_mfma_f32_16x16x32_bf16 v[216:219], v[164:167], v[184:187], v[42:45]
	s_setprio 0
	s_setprio 1
	v_mfma_f32_16x16x32_bf16 v[22:25], v[102:105], v[86:89], v[22:25]
	v_mfma_f32_16x16x32_bf16 v[18:21], v[118:121], v[86:89], v[18:21]
	v_mfma_f32_16x16x32_bf16 v[6:9], v[102:105], v[188:191], v[6:9]
	v_mfma_f32_16x16x32_bf16 v[2:5], v[118:121], v[188:191], v[2:5]
	v_mfma_f32_16x16x32_bf16 v[30:33], v[102:105], v[70:73], v[30:33]
	v_mfma_f32_16x16x32_bf16 v[26:29], v[118:121], v[70:73], v[26:29]
	v_mfma_f32_16x16x32_bf16 v[22:25], v[110:113], v[94:97], v[22:25]
	v_mfma_f32_16x16x32_bf16 v[18:21], v[208:211], v[94:97], v[18:21]
	v_mfma_f32_16x16x32_bf16 v[14:17], v[102:105], v[180:183], v[14:17]
	v_mfma_f32_16x16x32_bf16 v[10:13], v[118:121], v[180:183], v[10:13]
	v_mfma_f32_16x16x32_bf16 v[6:9], v[110:113], v[196:199], v[6:9]
	v_mfma_f32_16x16x32_bf16 v[2:5], v[208:211], v[196:199], v[2:5]
	v_mfma_f32_16x16x32_bf16 v[152:155], v[110:113], v[78:81], v[30:33]
	v_mfma_f32_16x16x32_bf16 v[156:159], v[208:211], v[78:81], v[26:29]
	v_mfma_f32_16x16x32_bf16 v[160:163], v[110:113], v[184:187], v[14:17]
	v_mfma_f32_16x16x32_bf16 v[164:167], v[208:211], v[184:187], v[10:13]
	s_barrier
	s_setprio 0
	s_nop 0
	ds_read_b128 v[10:13], v145
	ds_read_b128 v[14:17], v145 offset:1024
	ds_read_b128 v[180:183], v145 offset:2048
	ds_read_b128 v[144:147], v145 offset:3072
	ds_read_b128 v[26:29], v141 offset:32768
	ds_read_b128 v[30:33], v141 offset:33792
	ds_read_b128 v[42:45], v139 offset:32768
	ds_read_b128 v[46:49], v139 offset:33792
	ds_read_b128 v[184:187], v137 offset:32768
	ds_read_b128 v[188:191], v137 offset:33792
	ds_read_b128 v[196:199], v135 offset:32768
	ds_read_b128 v[208:211], v135 offset:33792
	s_waitcnt vmcnt(2)
	s_setprio 1
	s_barrier
	s_waitcnt lgkmcnt(0)
	v_mfma_f32_16x16x32_bf16 v[70:73], v[10:13], v[26:29], v[126:129]
	v_mfma_f32_16x16x32_bf16 v[126:129], v[14:17], v[30:33], v[70:73]
	v_mfma_f32_16x16x32_bf16 v[70:73], v[180:183], v[26:29], v[122:125]
	v_mfma_f32_16x16x32_bf16 v[118:121], v[144:147], v[30:33], v[70:73]
	v_mfma_f32_16x16x32_bf16 v[70:73], v[10:13], v[42:45], v[130:133]
	v_mfma_f32_16x16x32_bf16 v[110:113], v[14:17], v[46:49], v[70:73]
	v_mfma_f32_16x16x32_bf16 v[70:73], v[180:183], v[42:45], v[114:117]
	v_mfma_f32_16x16x32_bf16 v[102:105], v[144:147], v[46:49], v[70:73]
	v_mfma_f32_16x16x32_bf16 v[70:73], v[10:13], v[184:187], v[148:151]
	v_mfma_f32_16x16x32_bf16 v[94:97], v[14:17], v[188:191], v[70:73]
	v_mfma_f32_16x16x32_bf16 v[70:73], v[180:183], v[184:187], v[106:109]
	v_mfma_f32_16x16x32_bf16 v[86:89], v[144:147], v[188:191], v[70:73]
	v_mfma_f32_16x16x32_bf16 v[70:73], v[10:13], v[196:199], v[204:207]
	v_mfma_f32_16x16x32_bf16 v[78:81], v[14:17], v[208:211], v[70:73]
	v_mfma_f32_16x16x32_bf16 v[70:73], v[180:183], v[196:199], v[98:101]
	v_mfma_f32_16x16x32_bf16 v[70:73], v[144:147], v[208:211], v[70:73]
	s_barrier
;   #define LDA(dst,b,h) for(int m=0;m<4;++m)for(int k=0;k<2;++k) \
;     dst[m][k]=*reinterpret_cast<const bf16x8*>((char*)SA(b,h)+lds_byte(wr*64+m*16+fr,k*32+fq*8))
;   #define LDB(dst,b,h) for(int n=0;n<2;++n)for(int k=0;k<2;++k) \
;     dst[n][k]=*reinterpret_cast<const bf16x8*>((char*)SB(b,h)+lds_byte(wc*32+n*16+fr,k*32+fq*8))
;   #define MMA(ai,bj,At,Bt_) do{__builtin_amdgcn_s_setprio(1); \
;     for(int m=0;m<4;++m)for(int n=0;n<2;++n)for(int k=0;k<2;++k) \
;       acc[ai][bj][m][n]=__builtin_amdgcn_mfma_f32_16x16x32_bf16(Bt_[n][k],At[m][k],acc[ai][bj][m][n],0,0,0); \
;     __builtin_amdgcn_s_setprio(0);}while(0)
;   #define WAIT_V(n) asm volatile("s_waitcnt vmcnt(" #n ")":::"memory")
;   #define WAIT_L(n) asm volatile("s_waitcnt lgkmcnt(" #n ")":::"memory")
;   #define BAR __builtin_amdgcn_s_barrier()
; template <bool TWO, class MID> ...
;     ...
;     LDB(B1,1,1); WAIT_V(0); BAR; WAIT_L(0); MMA(0,1,At,B1); BAR;
;     LDA(At,1,1); BAR; WAIT_L(0); MMA(1,0,At,B0); MMA(1,1,At,B1); BAR; }
;   if(wr==0)BAR;
	s_setprio 0
	ds_read_b128 v[130:133], v143
	ds_read_b128 v[148:151], v143 offset:1024
	ds_read_b128 v[204:207], v143 offset:2048
	ds_read_b128 v[220:223], v143 offset:3072
	s_waitcnt vmcnt(0)
	s_setprio 1
	s_barrier
	s_waitcnt lgkmcnt(0)
	v_mfma_f32_16x16x32_bf16 v[98:101], v[130:133], v[26:29], v[212:215]
	v_mfma_f32_16x16x32_bf16 v[26:29], v[204:207], v[26:29], v[90:93]
	v_mfma_f32_16x16x32_bf16 v[114:117], v[220:223], v[30:33], v[26:29]
	v_mfma_f32_16x16x32_bf16 v[26:29], v[130:133], v[42:45], v[168:171]
	v_mfma_f32_16x16x32_bf16 v[106:109], v[148:151], v[46:49], v[26:29]
	v_mfma_f32_16x16x32_bf16 v[26:29], v[204:207], v[42:45], v[82:85]
	v_mfma_f32_16x16x32_bf16 v[122:125], v[148:151], v[30:33], v[98:101]
	v_mfma_f32_16x16x32_bf16 v[98:101], v[220:223], v[46:49], v[26:29]
	v_mfma_f32_16x16x32_bf16 v[26:29], v[130:133], v[184:187], v[172:175]
	v_mfma_f32_16x16x32_bf16 v[90:93], v[148:151], v[188:191], v[26:29]
	v_mfma_f32_16x16x32_bf16 v[26:29], v[204:207], v[184:187], v[74:77]
	v_mfma_f32_16x16x32_bf16 v[82:85], v[220:223], v[188:191], v[26:29]
	v_mfma_f32_16x16x32_bf16 v[26:29], v[130:133], v[196:199], v[176:179]
	v_mfma_f32_16x16x32_bf16 v[74:77], v[148:151], v[208:211], v[26:29]
	v_mfma_f32_16x16x32_bf16 v[26:29], v[204:207], v[196:199], v[66:69]
	v_mfma_f32_16x16x32_bf16 v[66:69], v[220:223], v[208:211], v[26:29]
	s_barrier
	s_setprio 0
	ds_read_b128 v[168:171], v141 offset:49152
	ds_read_b128 v[140:143], v141 offset:50176
	ds_read_b128 v[172:175], v139 offset:49152
	ds_read_b128 v[176:179], v139 offset:50176
	ds_read_b128 v[184:187], v137 offset:49152
	ds_read_b128 v[136:139], v137 offset:50176
	ds_read_b128 v[188:191], v135 offset:49152
	ds_read_b128 v[196:199], v135 offset:50176
	s_setprio 1
	s_barrier
	s_waitcnt lgkmcnt(0)
	v_mfma_f32_16x16x32_bf16 v[26:29], v[10:13], v[168:171], v[62:65]
	v_mfma_f32_16x16x32_bf16 v[62:65], v[14:17], v[140:143], v[26:29]
	v_mfma_f32_16x16x32_bf16 v[26:29], v[180:183], v[168:171], v[58:61]
	v_mfma_f32_16x16x32_bf16 v[58:61], v[144:147], v[140:143], v[26:29]
	v_mfma_f32_16x16x32_bf16 v[26:29], v[10:13], v[172:175], v[54:57]
	v_mfma_f32_16x16x32_bf16 v[46:49], v[14:17], v[176:179], v[26:29]
	v_mfma_f32_16x16x32_bf16 v[26:29], v[180:183], v[172:175], v[50:53]
	v_mfma_f32_16x16x32_bf16 v[42:45], v[144:147], v[176:179], v[26:29]
	v_mfma_f32_16x16x32_bf16 v[26:29], v[10:13], v[184:187], v[200:203]
	v_mfma_f32_16x16x32_bf16 v[10:13], v[10:13], v[188:191], v[38:41]
	v_mfma_f32_16x16x32_bf16 v[30:33], v[14:17], v[136:139], v[26:29]
	v_mfma_f32_16x16x32_bf16 v[26:29], v[180:183], v[184:187], v[216:219]
	v_mfma_f32_16x16x32_bf16 v[14:17], v[14:17], v[196:199], v[10:13]
	v_mfma_f32_16x16x32_bf16 v[10:13], v[180:183], v[188:191], v[34:37]
	v_mfma_f32_16x16x32_bf16 v[26:29], v[144:147], v[136:139], v[26:29]
	v_mfma_f32_16x16x32_bf16 v[10:13], v[144:147], v[196:199], v[10:13]
	s_setprio 0
	s_setprio 1
	v_mfma_f32_16x16x32_bf16 v[34:37], v[130:133], v[168:171], v[152:155]
	v_mfma_f32_16x16x32_bf16 v[54:57], v[148:151], v[140:143], v[34:37]
	v_mfma_f32_16x16x32_bf16 v[34:37], v[204:207], v[168:171], v[156:159]
	v_mfma_f32_16x16x32_bf16 v[18:21], v[204:207], v[172:175], v[18:21]
	v_mfma_f32_16x16x32_bf16 v[50:53], v[220:223], v[140:143], v[34:37]
	v_mfma_f32_16x16x32_bf16 v[22:25], v[130:133], v[172:175], v[22:25]
	v_mfma_f32_16x16x32_bf16 v[34:37], v[220:223], v[176:179], v[18:21]
	v_mfma_f32_16x16x32_bf16 v[18:21], v[130:133], v[184:187], v[160:163]
	v_mfma_f32_16x16x32_bf16 v[38:41], v[148:151], v[176:179], v[22:25]
	v_mfma_f32_16x16x32_bf16 v[22:25], v[148:151], v[136:139], v[18:21]
	v_mfma_f32_16x16x32_bf16 v[18:21], v[204:207], v[184:187], v[164:167]
	v_mfma_f32_16x16x32_bf16 v[6:9], v[130:133], v[188:191], v[6:9]
	v_mfma_f32_16x16x32_bf16 v[2:5], v[204:207], v[188:191], v[2:5]
	v_mfma_f32_16x16x32_bf16 v[18:21], v[220:223], v[136:139], v[18:21]
	v_mfma_f32_16x16x32_bf16 v[6:9], v[148:151], v[196:199], v[6:9]
	v_mfma_f32_16x16x32_bf16 v[2:5], v[220:223], v[196:199], v[2:5]
	s_setprio 0
	v_cmp_gt_u32_e32 vcc, s30, v1
	s_barrier
	s_and_saveexec_b64 s[4:5], vcc
	s_cbranch_execz .LBB0_565
	s_barrier

;   #define LDA(dst,b,h) for(int m=0;m<4;++m)for(int k=0;k<2;++k) \
;     dst[m][k]=*reinterpret_cast<const bf16x8*>((char*)SA(b,h)+lds_byte(wr*64+m*16+fr,k*32+fq*8))
;   #define LDB(dst,b,h) for(int n=0;n<2;++n)for(int k=0;k<2;++k) \
;     dst[n][k]=*reinterpret_cast<const bf16x8*>((char*)SB(b,h)+lds_byte(wc*32+n*16+fr,k*32+fq*8))
;   #define MMA(ai,bj,At,Bt_) do{__builtin_amdgcn_s_setprio(1); \
;     for(int m=0;m<4;++m)for(int n=0;n<2;++n)for(int k=0;k<2;++k) \
;       acc[ai][bj][m][n]=__builtin_amdgcn_mfma_f32_16x16x32_bf16(Bt_[n][k],At[m][k],acc[ai][bj][m][n],0,0,0); \
;     __builtin_amdgcn_s_setprio(0);}while(0)
;   #define WAIT_V(n) asm volatile("s_waitcnt vmcnt(" #n ")":::"memory")
;   #define WAIT_L(n) asm volatile("s_waitcnt lgkmcnt(" #n ")":::"memory")
;   #define BAR __builtin_amdgcn_s_barrier()
;   #define SCHED __builtin_amdgcn_sched_barrier(0)
; template <bool TWO, class MID> ...
;     ...
;     LDB(B0,0,0); SCHED; LDA(At,0,0); STAGE_A(SA(1,1),1,t+1);
;     WAIT_L(8); BAR; WAIT_L(0); MMA(0,0,At,B0); BAR; SCHED;
;     LDB(B1,0,1); STAGE_B(SB(0,0),0,t+2);
;     BAR; WAIT_L(0); MMA(0,1,At,B1); BAR;
;     LDA(At,0,1); STAGE_A(SA(0,0),0,t+2);
;     BAR; WAIT_L(0); MMA(1,0,At,B0); BAR; SCHED;
;     STAGE_B(SB(0,1),1,t+2);
;     WAIT_V(6); BAR; MMA(1,1,At,B1); BAR;
.LBB0_620:
	ds_read_b128 v[166:169], v149
	ds_read_b128 v[170:173], v149 offset:1024
	ds_read_b128 v[174:177], v149 offset:2048
	ds_read_b128 v[178:181], v149 offset:3072
	ds_read_b128 v[182:185], v141
	ds_read_b128 v[186:189], v141 offset:1024
	ds_read_b128 v[190:193], v139
	ds_read_b128 v[196:199], v139 offset:1024
	ds_read_b128 v[200:203], v137
	ds_read_b128 v[204:207], v137 offset:1024
	ds_read_b128 v[208:211], v135
	ds_read_b128 v[212:215], v135 offset:1024
	s_add_u32 s15, s0, s16
	s_addc_u32 s18, s1, s17
	s_add_u32 m0, s98, 0xc000
	s_add_u32 s24, s15, 0x10200080
	s_addc_u32 s25, s18, 0
	global_load_lds_dwordx4 v132, s[24:25]
	s_add_u32 m0, s98, 0xe000
	s_setprio 1
	global_load_lds_dwordx4 v130, s[24:25]
	s_waitcnt lgkmcnt(8)
	s_barrier
	s_waitcnt lgkmcnt(0)
	v_mfma_f32_16x16x32_bf16 v[126:129], v[166:169], v[182:185], v[126:129]
	v_mfma_f32_16x16x32_bf16 v[122:125], v[174:177], v[182:185], v[122:125]
	v_mfma_f32_16x16x32_bf16 v[118:121], v[166:169], v[190:193], v[118:121]
	v_mfma_f32_16x16x32_bf16 v[114:117], v[174:177], v[190:193], v[114:117]
	v_mfma_f32_16x16x32_bf16 v[110:113], v[166:169], v[200:203], v[110:113]
	v_mfma_f32_16x16x32_bf16 v[106:109], v[174:177], v[200:203], v[106:109]
	v_mfma_f32_16x16x32_bf16 v[102:105], v[166:169], v[208:211], v[102:105]
	v_mfma_f32_16x16x32_bf16 v[98:101], v[174:177], v[208:211], v[98:101]
	v_mfma_f32_16x16x32_bf16 v[126:129], v[170:173], v[186:189], v[126:129]
	v_mfma_f32_16x16x32_bf16 v[122:125], v[178:181], v[186:189], v[122:125]
	v_mfma_f32_16x16x32_bf16 v[118:121], v[170:173], v[196:199], v[118:121]
	v_mfma_f32_16x16x32_bf16 v[114:117], v[178:181], v[196:199], v[114:117]
	v_mfma_f32_16x16x32_bf16 v[110:113], v[170:173], v[204:207], v[110:113]
	v_mfma_f32_16x16x32_bf16 v[106:109], v[178:181], v[204:207], v[106:109]
	v_mfma_f32_16x16x32_bf16 v[102:105], v[170:173], v[212:215], v[102:105]
	v_mfma_f32_16x16x32_bf16 v[98:101], v[178:181], v[212:215], v[98:101]
	s_barrier
	s_setprio 0
	s_add_u32 s19, s0, s4
	ds_read_b128 v[216:219], v147
	ds_read_b128 v[220:223], v147 offset:1024
	ds_read_b128 v[224:227], v147 offset:2048
	ds_read_b128 v[228:231], v147 offset:3072
	s_addc_u32 s24, s1, s5
	s_add_u32 m0, s98, 0x10000
	s_add_u32 s26, s19, 0x5c00100
	s_addc_u32 s27, s24, 0
	global_load_lds_dwordx4 v132, s[26:27]
	s_add_u32 m0, s98, 0x12000
	s_setprio 1
	global_load_lds_dwordx4 v130, s[26:27]
	s_barrier
	s_waitcnt lgkmcnt(0)
	v_mfma_f32_16x16x32_bf16 v[94:97], v[216:219], v[182:185], v[94:97]
	v_mfma_f32_16x16x32_bf16 v[90:93], v[224:227], v[182:185], v[90:93]
	v_mfma_f32_16x16x32_bf16 v[86:89], v[216:219], v[190:193], v[86:89]
	v_mfma_f32_16x16x32_bf16 v[82:85], v[224:227], v[190:193], v[82:85]
	v_mfma_f32_16x16x32_bf16 v[78:81], v[216:219], v[200:203], v[78:81]
	v_mfma_f32_16x16x32_bf16 v[74:77], v[224:227], v[200:203], v[74:77]
	v_mfma_f32_16x16x32_bf16 v[70:73], v[216:219], v[208:211], v[70:73]
	v_mfma_f32_16x16x32_bf16 v[66:69], v[224:227], v[208:211], v[66:69]
	v_mfma_f32_16x16x32_bf16 v[94:97], v[220:223], v[186:189], v[94:97]
	v_mfma_f32_16x16x32_bf16 v[90:93], v[228:231], v[186:189], v[90:93]
	v_mfma_f32_16x16x32_bf16 v[86:89], v[220:223], v[196:199], v[86:89]
	v_mfma_f32_16x16x32_bf16 v[82:85], v[228:231], v[196:199], v[82:85]
	v_mfma_f32_16x16x32_bf16 v[78:81], v[220:223], v[204:207], v[78:81]
	v_mfma_f32_16x16x32_bf16 v[74:77], v[228:231], v[204:207], v[74:77]
	v_mfma_f32_16x16x32_bf16 v[70:73], v[220:223], v[212:215], v[70:73]
	v_mfma_f32_16x16x32_bf16 v[66:69], v[228:231], v[212:215], v[66:69]
	s_barrier
	s_setprio 0
	ds_read_b128 v[182:185], v141 offset:16384
	ds_read_b128 v[186:189], v141 offset:17408
	ds_read_b128 v[190:193], v139 offset:16384
	ds_read_b128 v[196:199], v139 offset:17408
	ds_read_b128 v[200:203], v137 offset:16384
	ds_read_b128 v[204:207], v137 offset:17408
	ds_read_b128 v[208:211], v135 offset:16384
	ds_read_b128 v[212:215], v135 offset:17408
	s_add_u32 m0, s98, 0x0
	s_add_u32 s26, s15, 0x10000100
	s_addc_u32 s27, s18, 0
	global_load_lds_dwordx4 v132, s[26:27]
	s_add_u32 m0, s98, 0x2000
	s_setprio 1
	global_load_lds_dwordx4 v130, s[26:27]
	s_barrier
	s_waitcnt lgkmcnt(0)
	v_mfma_f32_16x16x32_bf16 v[62:65], v[166:169], v[182:185], v[62:65]
	v_mfma_f32_16x16x32_bf16 v[58:61], v[174:177], v[182:185], v[58:61]
	v_mfma_f32_16x16x32_bf16 v[54:57], v[166:169], v[190:193], v[54:57]
	v_mfma_f32_16x16x32_bf16 v[50:53], v[174:177], v[190:193], v[50:53]
	v_mfma_f32_16x16x32_bf16 v[46:49], v[166:169], v[200:203], v[46:49]
	v_mfma_f32_16x16x32_bf16 v[42:45], v[174:177], v[200:203], v[42:45]
	v_mfma_f32_16x16x32_bf16 v[38:41], v[166:169], v[208:211], v[38:41]
	v_mfma_f32_16x16x32_bf16 v[34:37], v[174:177], v[208:211], v[34:37]
	v_mfma_f32_16x16x32_bf16 v[62:65], v[170:173], v[186:189], v[62:65]
	v_mfma_f32_16x16x32_bf16 v[58:61], v[178:181], v[186:189], v[58:61]
	v_mfma_f32_16x16x32_bf16 v[54:57], v[170:173], v[196:199], v[54:57]
	v_mfma_f32_16x16x32_bf16 v[50:53], v[178:181], v[196:199], v[50:53]
	v_mfma_f32_16x16x32_bf16 v[46:49], v[170:173], v[204:207], v[46:49]
	v_mfma_f32_16x16x32_bf16 v[42:45], v[178:181], v[204:207], v[42:45]
	v_mfma_f32_16x16x32_bf16 v[38:41], v[170:173], v[212:215], v[38:41]
	v_mfma_f32_16x16x32_bf16 v[34:37], v[178:181], v[212:215], v[34:37]
	s_barrier
	s_setprio 0
	s_add_u32 m0, s98, 0x14000
	s_add_u32 s26, s19, 0x5e00100
	s_addc_u32 s27, s24, 0
	global_load_lds_dwordx4 v132, s[26:27]
	s_add_u32 m0, s98, 0x16000
	s_setprio 1
	global_load_lds_dwordx4 v130, s[26:27]
	s_waitcnt vmcnt(6)
	s_barrier
;   #define LDA(dst,b,h) for(int m=0;m<4;++m)for(int k=0;k<2;++k) \
;     dst[m][k]=*reinterpret_cast<const bf16x8*>((char*)SA(b,h)+lds_byte(wr*64+m*16+fr,k*32+fq*8))
;   #define LDB(dst,b,h) for(int n=0;n<2;++n)for(int k=0;k<2;++k) \
;     dst[n][k]=*reinterpret_cast<const bf16x8*>((char*)SB(b,h)+lds_byte(wc*32+n*16+fr,k*32+fq*8))
;   #define MMA(ai,bj,At,Bt_) do{__builtin_amdgcn_s_setprio(1); \
;     for(int m=0;m<4;++m)for(int n=0;n<2;++n)for(int k=0;k<2;++k) \
;       acc[ai][bj][m][n]=__builtin_amdgcn_mfma_f32_16x16x32_bf16(Bt_[n][k],At[m][k],acc[ai][bj][m][n],0,0,0); \
;     __builtin_amdgcn_s_setprio(0);}while(0)
;   #define WAIT_V(n) asm volatile("s_waitcnt vmcnt(" #n ")":::"memory")
;   #define WAIT_L(n) asm volatile("s_waitcnt lgkmcnt(" #n ")":::"memory")
;   #define BAR __builtin_amdgcn_s_barrier()
;   #define SCHED __builtin_amdgcn_sched_barrier(0)
; template <bool TWO, class MID> ...
;     ...
;     WAIT_V(6); BAR; MMA(1,1,At,B1); BAR;
;     LDB(B0,1,0); SCHED; LDA(At,1,0); STAGE_A(SA(0,1),1,t+2);
;     WAIT_L(8); BAR; WAIT_L(0); MMA(0,0,At,B0); BAR; SCHED;
;     LDB(B1,1,1); STAGE_B(SB(1,0),0,t+3);
;     BAR; WAIT_L(0); MMA(0,1,At,B1); BAR;
;     LDA(At,1,1); STAGE_A(SA(1,0),0,t+3);
	v_mfma_f32_16x16x32_bf16 v[30:33], v[216:219], v[182:185], v[30:33]
	v_mfma_f32_16x16x32_bf16 v[26:29], v[224:227], v[182:185], v[26:29]
	v_mfma_f32_16x16x32_bf16 v[22:25], v[216:219], v[190:193], v[22:25]
	v_mfma_f32_16x16x32_bf16 v[18:21], v[224:227], v[190:193], v[18:21]
	v_mfma_f32_16x16x32_bf16 v[14:17], v[216:219], v[200:203], v[14:17]
	v_mfma_f32_16x16x32_bf16 v[10:13], v[224:227], v[200:203], v[10:13]
	v_mfma_f32_16x16x32_bf16 v[6:9], v[216:219], v[208:211], v[6:9]
	v_mfma_f32_16x16x32_bf16 v[2:5], v[224:227], v[208:211], v[2:5]
	v_mfma_f32_16x16x32_bf16 v[30:33], v[220:223], v[186:189], v[30:33]
	v_mfma_f32_16x16x32_bf16 v[26:29], v[228:231], v[186:189], v[26:29]
	v_mfma_f32_16x16x32_bf16 v[22:25], v[220:223], v[196:199], v[22:25]
	v_mfma_f32_16x16x32_bf16 v[18:21], v[228:231], v[196:199], v[18:21]
	v_mfma_f32_16x16x32_bf16 v[14:17], v[220:223], v[204:207], v[14:17]
	v_mfma_f32_16x16x32_bf16 v[10:13], v[228:231], v[204:207], v[10:13]
	v_mfma_f32_16x16x32_bf16 v[6:9], v[220:223], v[212:215], v[6:9]
	v_mfma_f32_16x16x32_bf16 v[2:5], v[228:231], v[212:215], v[2:5]
	s_barrier
	s_setprio 0
	ds_read_b128 v[166:169], v145
	ds_read_b128 v[170:173], v145 offset:1024
	ds_read_b128 v[174:177], v145 offset:2048
	ds_read_b128 v[178:181], v145 offset:3072
	ds_read_b128 v[182:185], v141 offset:32768
	ds_read_b128 v[186:189], v141 offset:33792
	ds_read_b128 v[190:193], v139 offset:32768
	ds_read_b128 v[196:199], v139 offset:33792
	ds_read_b128 v[200:203], v137 offset:32768
	ds_read_b128 v[204:207], v137 offset:33792
	ds_read_b128 v[208:211], v135 offset:32768
	ds_read_b128 v[212:215], v135 offset:33792
	s_add_u32 m0, s98, 0x4000
	s_add_u32 s26, s15, 0x10200100
	s_addc_u32 s27, s18, 0
	global_load_lds_dwordx4 v132, s[26:27]
	s_add_u32 m0, s98, 0x6000
	s_setprio 1
	global_load_lds_dwordx4 v130, s[26:27]
	s_waitcnt lgkmcnt(8)
	s_barrier
	s_waitcnt lgkmcnt(0)
	v_mfma_f32_16x16x32_bf16 v[126:129], v[166:169], v[182:185], v[126:129]
	v_mfma_f32_16x16x32_bf16 v[122:125], v[174:177], v[182:185], v[122:125]
	v_mfma_f32_16x16x32_bf16 v[118:121], v[166:169], v[190:193], v[118:121]
	v_mfma_f32_16x16x32_bf16 v[114:117], v[174:177], v[190:193], v[114:117]
	v_mfma_f32_16x16x32_bf16 v[110:113], v[166:169], v[200:203], v[110:113]
	v_mfma_f32_16x16x32_bf16 v[106:109], v[174:177], v[200:203], v[106:109]
	v_mfma_f32_16x16x32_bf16 v[102:105], v[166:169], v[208:211], v[102:105]
	v_mfma_f32_16x16x32_bf16 v[98:101], v[174:177], v[208:211], v[98:101]
	v_mfma_f32_16x16x32_bf16 v[126:129], v[170:173], v[186:189], v[126:129]
	v_mfma_f32_16x16x32_bf16 v[122:125], v[178:181], v[186:189], v[122:125]
	v_mfma_f32_16x16x32_bf16 v[118:121], v[170:173], v[196:199], v[118:121]
	v_mfma_f32_16x16x32_bf16 v[114:117], v[178:181], v[196:199], v[114:117]
	v_mfma_f32_16x16x32_bf16 v[110:113], v[170:173], v[204:207], v[110:113]
	v_mfma_f32_16x16x32_bf16 v[106:109], v[178:181], v[204:207], v[106:109]
	v_mfma_f32_16x16x32_bf16 v[102:105], v[170:173], v[212:215], v[102:105]
	v_mfma_f32_16x16x32_bf16 v[98:101], v[178:181], v[212:215], v[98:101]
	s_barrier
	s_setprio 0
	ds_read_b128 v[216:219], v143
	ds_read_b128 v[220:223], v143 offset:1024
	ds_read_b128 v[224:227], v143 offset:2048
	ds_read_b128 v[228:231], v143 offset:3072
	s_add_u32 m0, s98, 0x18000
	s_add_u32 s26, s19, 0x5c00180
	s_addc_u32 s27, s24, 0
	global_load_lds_dwordx4 v132, s[26:27]
	s_add_u32 m0, s98, 0x1a000
	s_setprio 1
	global_load_lds_dwordx4 v130, s[26:27]
	s_barrier
	s_waitcnt lgkmcnt(0)
	v_mfma_f32_16x16x32_bf16 v[94:97], v[216:219], v[182:185], v[94:97]
	v_mfma_f32_16x16x32_bf16 v[90:93], v[224:227], v[182:185], v[90:93]
	v_mfma_f32_16x16x32_bf16 v[86:89], v[216:219], v[190:193], v[86:89]
	v_mfma_f32_16x16x32_bf16 v[82:85], v[224:227], v[190:193], v[82:85]
	v_mfma_f32_16x16x32_bf16 v[78:81], v[216:219], v[200:203], v[78:81]
	v_mfma_f32_16x16x32_bf16 v[74:77], v[224:227], v[200:203], v[74:77]
	v_mfma_f32_16x16x32_bf16 v[70:73], v[216:219], v[208:211], v[70:73]
	v_mfma_f32_16x16x32_bf16 v[66:69], v[224:227], v[208:211], v[66:69]
	v_mfma_f32_16x16x32_bf16 v[94:97], v[220:223], v[186:189], v[94:97]
	v_mfma_f32_16x16x32_bf16 v[90:93], v[228:231], v[186:189], v[90:93]
	v_mfma_f32_16x16x32_bf16 v[86:89], v[220:223], v[196:199], v[86:89]
	v_mfma_f32_16x16x32_bf16 v[82:85], v[228:231], v[196:199], v[82:85]
	v_mfma_f32_16x16x32_bf16 v[78:81], v[220:223], v[204:207], v[78:81]
	v_mfma_f32_16x16x32_bf16 v[74:77], v[228:231], v[204:207], v[74:77]
	v_mfma_f32_16x16x32_bf16 v[70:73], v[220:223], v[212:215], v[70:73]
	v_mfma_f32_16x16x32_bf16 v[66:69], v[228:231], v[212:215], v[66:69]
	s_barrier
	s_setprio 0
	ds_read_b128 v[182:185], v141 offset:49152
	ds_read_b128 v[186:189], v141 offset:50176
	ds_read_b128 v[190:193], v139 offset:49152
	ds_read_b128 v[196:199], v139 offset:50176
	ds_read_b128 v[200:203], v137 offset:49152
	ds_read_b128 v[204:207], v137 offset:50176
	ds_read_b128 v[208:211], v135 offset:49152
	ds_read_b128 v[212:215], v135 offset:50176
	s_add_u32 m0, s98, 0x8000
	s_add_u32 s26, s15, 0x10000180
	s_addc_u32 s27, s18, 0
	global_load_lds_dwordx4 v132, s[26:27]
	s_add_u32 m0, s98, 0xa000
	s_setprio 1
	global_load_lds_dwordx4 v130, s[26:27]
	s_barrier
;   #define LDA(dst,b,h) for(int m=0;m<4;++m)for(int k=0;k<2;++k) \
;     dst[m][k]=*reinterpret_cast<const bf16x8*>((char*)SA(b,h)+lds_byte(wr*64+m*16+fr,k*32+fq*8))
;   #define LDB(dst,b,h) for(int n=0;n<2;++n)for(int k=0;k<2;++k) \
;     dst[n][k]=*reinterpret_cast<const bf16x8*>((char*)SB(b,h)+lds_byte(wc*32+n*16+fr,k*32+fq*8))
;   #define MMA(ai,bj,At,Bt_) do{__builtin_amdgcn_s_setprio(1); \
;     for(int m=0;m<4;++m)for(int n=0;n<2;++n)for(int k=0;k<2;++k) \
;       acc[ai][bj][m][n]=__builtin_amdgcn_mfma_f32_16x16x32_bf16(Bt_[n][k],At[m][k],acc[ai][bj][m][n],0,0,0); \
;     __builtin_amdgcn_s_setprio(0);}while(0)
;   #define WAIT_V(n) asm volatile("s_waitcnt vmcnt(" #n ")":::"memory")
;   #define WAIT_L(n) asm volatile("s_waitcnt lgkmcnt(" #n ")":::"memory")
;   #define BAR __builtin_amdgcn_s_barrier()
;   #define SCHED __builtin_amdgcn_sched_barrier(0)
; template <bool TWO, class MID> ...
;     ...
;     BAR; WAIT_L(0); MMA(1,0,At,B0); BAR; SCHED;
;     STAGE_B(SB(1,1),1,t+3);
;     WAIT_V(6); BAR; MMA(1,1,At,B1); BAR;
;   }
;   { LDB(B0,0,0); LDA(At,0,0); STAGE_A(SA(1,1),1,nt-1);
;     BAR; WAIT_L(0); MMA(0,0,At,B0); BAR;
;     LDB(B1,0,1); BAR; WAIT_L(0); MMA(0,1,At,B1); BAR;
	s_waitcnt lgkmcnt(0)
	v_mfma_f32_16x16x32_bf16 v[62:65], v[166:169], v[182:185], v[62:65]
	v_mfma_f32_16x16x32_bf16 v[58:61], v[174:177], v[182:185], v[58:61]
	v_mfma_f32_16x16x32_bf16 v[54:57], v[166:169], v[190:193], v[54:57]
	v_mfma_f32_16x16x32_bf16 v[50:53], v[174:177], v[190:193], v[50:53]
	v_mfma_f32_16x16x32_bf16 v[46:49], v[166:169], v[200:203], v[46:49]
	v_mfma_f32_16x16x32_bf16 v[42:45], v[174:177], v[200:203], v[42:45]
	v_mfma_f32_16x16x32_bf16 v[38:41], v[166:169], v[208:211], v[38:41]
	v_mfma_f32_16x16x32_bf16 v[34:37], v[174:177], v[208:211], v[34:37]
	v_mfma_f32_16x16x32_bf16 v[62:65], v[170:173], v[186:189], v[62:65]
	v_mfma_f32_16x16x32_bf16 v[58:61], v[178:181], v[186:189], v[58:61]
	v_mfma_f32_16x16x32_bf16 v[54:57], v[170:173], v[196:199], v[54:57]
	v_mfma_f32_16x16x32_bf16 v[50:53], v[178:181], v[196:199], v[50:53]
	v_mfma_f32_16x16x32_bf16 v[46:49], v[170:173], v[204:207], v[46:49]
	v_mfma_f32_16x16x32_bf16 v[42:45], v[178:181], v[204:207], v[42:45]
	v_mfma_f32_16x16x32_bf16 v[38:41], v[170:173], v[212:215], v[38:41]
	v_mfma_f32_16x16x32_bf16 v[34:37], v[178:181], v[212:215], v[34:37]
	s_barrier
	s_setprio 0
	s_add_u32 m0, s98, 0x1c000
	s_add_u32 s18, s19, 0x5e00180
	s_addc_u32 s19, s24, 0
	global_load_lds_dwordx4 v132, s[18:19]
	s_add_u32 m0, s98, 0x1e000
	s_setprio 1
	global_load_lds_dwordx4 v130, s[18:19]
	s_waitcnt vmcnt(6)
	s_barrier
	v_mfma_f32_16x16x32_bf16 v[30:33], v[216:219], v[182:185], v[30:33]
	v_mfma_f32_16x16x32_bf16 v[26:29], v[224:227], v[182:185], v[26:29]
	v_mfma_f32_16x16x32_bf16 v[22:25], v[216:219], v[190:193], v[22:25]
	v_mfma_f32_16x16x32_bf16 v[18:21], v[224:227], v[190:193], v[18:21]
	v_mfma_f32_16x16x32_bf16 v[14:17], v[216:219], v[200:203], v[14:17]
	v_mfma_f32_16x16x32_bf16 v[10:13], v[224:227], v[200:203], v[10:13]
	v_mfma_f32_16x16x32_bf16 v[6:9], v[216:219], v[208:211], v[6:9]
	v_mfma_f32_16x16x32_bf16 v[2:5], v[224:227], v[208:211], v[2:5]
	v_mfma_f32_16x16x32_bf16 v[30:33], v[220:223], v[186:189], v[30:33]
	v_mfma_f32_16x16x32_bf16 v[26:29], v[228:231], v[186:189], v[26:29]
	v_mfma_f32_16x16x32_bf16 v[22:25], v[220:223], v[196:199], v[22:25]
	v_mfma_f32_16x16x32_bf16 v[18:21], v[228:231], v[196:199], v[18:21]
	v_mfma_f32_16x16x32_bf16 v[14:17], v[220:223], v[204:207], v[14:17]
	v_mfma_f32_16x16x32_bf16 v[10:13], v[228:231], v[204:207], v[10:13]
	v_mfma_f32_16x16x32_bf16 v[6:9], v[220:223], v[212:215], v[6:9]
	v_mfma_f32_16x16x32_bf16 v[2:5], v[228:231], v[212:215], v[2:5]
	s_barrier
	s_setprio 0
	s_add_i32 s14, s14, 2
	s_add_u32 s0, s0, 0x100
	s_addc_u32 s1, s1, 0
	s_cmpk_lt_u32 s14, 0x7c
	s_cbranch_scc1 .LBB0_620
	ds_read_b128 v[152:155], v149
	ds_read_b128 v[156:159], v149 offset:1024
	ds_read_b128 v[160:163], v149 offset:2048
	ds_read_b128 v[164:167], v149 offset:3072
	ds_read_b128 v[168:171], v141
	ds_read_b128 v[172:175], v141 offset:1024
	ds_read_b128 v[176:179], v139
	ds_read_b128 v[180:183], v139 offset:1024
	ds_read_b128 v[184:187], v137
	ds_read_b128 v[188:191], v137 offset:1024
	ds_read_b128 v[196:199], v135
	ds_read_b128 v[200:203], v135 offset:1024
	s_add_u32 s0, s12, 0x203f80
	s_addc_u32 s1, s13, 0
	v_lshl_add_u64 v[132:133], s[0:1], 0, v[132:133]
	v_readfirstlane_b32 s12, v148
	s_mov_b32 m0, s12
	global_load_lds_dwordx4 v[132:133], off
	v_lshl_add_u64 v[130:131], s[0:1], 0, v[130:131]
	v_readfirstlane_b32 s0, v150
	s_mov_b32 m0, s0
	global_load_lds_dwordx4 v[130:131], off
	s_setprio 1
	s_barrier
	s_waitcnt lgkmcnt(0)
	v_mfma_f32_16x16x32_bf16 v[126:129], v[152:155], v[168:171], v[126:129]
	v_mfma_f32_16x16x32_bf16 v[122:125], v[160:163], v[168:171], v[122:125]
	v_mfma_f32_16x16x32_bf16 v[118:121], v[152:155], v[176:179], v[118:121]
	v_mfma_f32_16x16x32_bf16 v[114:117], v[160:163], v[176:179], v[114:117]
	v_mfma_f32_16x16x32_bf16 v[102:105], v[152:155], v[196:199], v[102:105]
	v_mfma_f32_16x16x32_bf16 v[98:101], v[160:163], v[196:199], v[98:101]
	v_mfma_f32_16x16x32_bf16 v[126:129], v[156:159], v[172:175], v[126:129]
	v_mfma_f32_16x16x32_bf16 v[122:125], v[164:167], v[172:175], v[122:125]
	v_mfma_f32_16x16x32_bf16 v[118:121], v[156:159], v[180:183], v[118:121]
	v_mfma_f32_16x16x32_bf16 v[114:117], v[164:167], v[180:183], v[114:117]
	v_mfma_f32_16x16x32_bf16 v[110:113], v[152:155], v[184:187], v[110:113]
	v_mfma_f32_16x16x32_bf16 v[106:109], v[160:163], v[184:187], v[106:109]
	v_mfma_f32_16x16x32_bf16 v[102:105], v[156:159], v[200:203], v[102:105]
	v_mfma_f32_16x16x32_bf16 v[98:101], v[164:167], v[200:203], v[98:101]
	v_mfma_f32_16x16x32_bf16 v[130:133], v[156:159], v[188:191], v[110:113]
	v_mfma_f32_16x16x32_bf16 v[148:151], v[164:167], v[188:191], v[106:109]
	s_barrier
	s_setprio 0
	s_nop 0
	ds_read_b128 v[106:109], v147
	ds_read_b128 v[110:113], v147 offset:1024
	ds_read_b128 v[204:207], v147 offset:2048
	ds_read_b128 v[208:211], v147 offset:3072
	s_setprio 1
	s_barrier
	s_waitcnt lgkmcnt(0)
	v_mfma_f32_16x16x32_bf16 v[86:89], v[106:109], v[176:179], v[86:89]
	v_mfma_f32_16x16x32_bf16 v[82:85], v[204:207], v[176:179], v[82:85]
	v_mfma_f32_16x16x32_bf16 v[70:73], v[106:109], v[196:199], v[70:73]
	v_mfma_f32_16x16x32_bf16 v[66:69], v[204:207], v[196:199], v[66:69]
	v_mfma_f32_16x16x32_bf16 v[94:97], v[106:109], v[168:171], v[94:97]
	v_mfma_f32_16x16x32_bf16 v[90:93], v[204:207], v[168:171], v[90:93]
	v_mfma_f32_16x16x32_bf16 v[86:89], v[110:113], v[180:183], v[86:89]
	v_mfma_f32_16x16x32_bf16 v[82:85], v[208:211], v[180:183], v[82:85]
	v_mfma_f32_16x16x32_bf16 v[78:81], v[106:109], v[184:187], v[78:81]
	v_mfma_f32_16x16x32_bf16 v[74:77], v[204:207], v[184:187], v[74:77]
	v_mfma_f32_16x16x32_bf16 v[70:73], v[110:113], v[200:203], v[70:73]
	v_mfma_f32_16x16x32_bf16 v[66:69], v[208:211], v[200:203], v[66:69]
	v_mfma_f32_16x16x32_bf16 v[212:215], v[110:113], v[172:175], v[94:97]
	v_mfma_f32_16x16x32_bf16 v[168:171], v[208:211], v[172:175], v[90:93]
	v_mfma_f32_16x16x32_bf16 v[172:175], v[110:113], v[188:191], v[78:81]
	v_mfma_f32_16x16x32_bf16 v[176:179], v[208:211], v[188:191], v[74:77]
	s_barrier
;   #define LDA(dst,b,h) for(int m=0;m<4;++m)for(int k=0;k<2;++k) \
;     dst[m][k]=*reinterpret_cast<const bf16x8*>((char*)SA(b,h)+lds_byte(wr*64+m*16+fr,k*32+fq*8))
;   #define LDB(dst,b,h) for(int n=0;n<2;++n)for(int k=0;k<2;++k) \
;     dst[n][k]=*reinterpret_cast<const bf16x8*>((char*)SB(b,h)+lds_byte(wc*32+n*16+fr,k*32+fq*8))
;   #define MMA(ai,bj,At,Bt_) do{__builtin_amdgcn_s_setprio(1); \
;     for(int m=0;m<4;++m)for(int n=0;n<2;++n)for(int k=0;k<2;++k) \
;       acc[ai][bj][m][n]=__builtin_amdgcn_mfma_f32_16x16x32_bf16(Bt_[n][k],At[m][k],acc[ai][bj][m][n],0,0,0); \
;     __builtin_amdgcn_s_setprio(0);}while(0)
;   #define WAIT_V(n) asm volatile("s_waitcnt vmcnt(" #n ")":::"memory")
;   #define WAIT_L(n) asm volatile("s_waitcnt lgkmcnt(" #n ")":::"memory")
;   #define BAR __builtin_amdgcn_s_barrier()
; template <bool TWO, class MID> ...
;     ...
;     LDA(At,0,1); WAIT_V(4); BAR; WAIT_L(0); MMA(1,0,At,B0); MMA(1,1,At,B1); BAR; }
;   { LDB(B0,1,0); LDA(At,1,0); WAIT_V(2); BAR; WAIT_L(0); MMA(0,0,At,B0); BAR;
	s_setprio 0
	s_nop 0
	ds_read_b128 v[74:77], v141 offset:16384
	ds_read_b128 v[78:81], v141 offset:17408
	ds_read_b128 v[90:93], v139 offset:16384
	ds_read_b128 v[94:97], v139 offset:17408
	ds_read_b128 v[180:183], v137 offset:16384
	ds_read_b128 v[184:187], v137 offset:17408
	ds_read_b128 v[188:191], v135 offset:16384
	ds_read_b128 v[196:199], v135 offset:17408
	s_waitcnt vmcnt(4)
	s_setprio 1
	s_barrier
	s_waitcnt lgkmcnt(0)
	v_mfma_f32_16x16x32_bf16 v[62:65], v[152:155], v[74:77], v[62:65]
	v_mfma_f32_16x16x32_bf16 v[58:61], v[160:163], v[74:77], v[58:61]
	v_mfma_f32_16x16x32_bf16 v[54:57], v[152:155], v[90:93], v[54:57]
	v_mfma_f32_16x16x32_bf16 v[50:53], v[160:163], v[90:93], v[50:53]
	v_mfma_f32_16x16x32_bf16 v[38:41], v[152:155], v[188:191], v[38:41]
	v_mfma_f32_16x16x32_bf16 v[34:37], v[160:163], v[188:191], v[34:37]
	v_mfma_f32_16x16x32_bf16 v[62:65], v[156:159], v[78:81], v[62:65]
	v_mfma_f32_16x16x32_bf16 v[58:61], v[164:167], v[78:81], v[58:61]
	v_mfma_f32_16x16x32_bf16 v[54:57], v[156:159], v[94:97], v[54:57]
	v_mfma_f32_16x16x32_bf16 v[50:53], v[164:167], v[94:97], v[50:53]
	v_mfma_f32_16x16x32_bf16 v[46:49], v[152:155], v[180:183], v[46:49]
	v_mfma_f32_16x16x32_bf16 v[42:45], v[160:163], v[180:183], v[42:45]
	v_mfma_f32_16x16x32_bf16 v[38:41], v[156:159], v[196:199], v[38:41]
	v_mfma_f32_16x16x32_bf16 v[34:37], v[164:167], v[196:199], v[34:37]
	v_mfma_f32_16x16x32_bf16 v[200:203], v[156:159], v[184:187], v[46:49]
	v_mfma_f32_16x16x32_bf16 v[216:219], v[164:167], v[184:187], v[42:45]
	s_setprio 0
	s_setprio 1
	v_mfma_f32_16x16x32_bf16 v[22:25], v[106:109], v[90:93], v[22:25]
	v_mfma_f32_16x16x32_bf16 v[18:21], v[204:207], v[90:93], v[18:21]
	v_mfma_f32_16x16x32_bf16 v[6:9], v[106:109], v[188:191], v[6:9]
	v_mfma_f32_16x16x32_bf16 v[2:5], v[204:207], v[188:191], v[2:5]
	v_mfma_f32_16x16x32_bf16 v[30:33], v[106:109], v[74:77], v[30:33]
	v_mfma_f32_16x16x32_bf16 v[26:29], v[204:207], v[74:77], v[26:29]
	v_mfma_f32_16x16x32_bf16 v[22:25], v[110:113], v[94:97], v[22:25]
	v_mfma_f32_16x16x32_bf16 v[18:21], v[208:211], v[94:97], v[18:21]
	v_mfma_f32_16x16x32_bf16 v[14:17], v[106:109], v[180:183], v[14:17]
	v_mfma_f32_16x16x32_bf16 v[10:13], v[204:207], v[180:183], v[10:13]
	v_mfma_f32_16x16x32_bf16 v[6:9], v[110:113], v[196:199], v[6:9]
	v_mfma_f32_16x16x32_bf16 v[2:5], v[208:211], v[196:199], v[2:5]
	v_mfma_f32_16x16x32_bf16 v[152:155], v[110:113], v[78:81], v[30:33]
	v_mfma_f32_16x16x32_bf16 v[156:159], v[208:211], v[78:81], v[26:29]
	v_mfma_f32_16x16x32_bf16 v[160:163], v[110:113], v[184:187], v[14:17]
	v_mfma_f32_16x16x32_bf16 v[164:167], v[208:211], v[184:187], v[10:13]
	s_barrier
	s_setprio 0
	s_nop 0
	ds_read_b128 v[10:13], v145
	ds_read_b128 v[14:17], v145 offset:1024
	ds_read_b128 v[180:183], v145 offset:2048
	ds_read_b128 v[144:147], v145 offset:3072
	ds_read_b128 v[26:29], v141 offset:32768
	ds_read_b128 v[30:33], v141 offset:33792
	ds_read_b128 v[42:45], v139 offset:32768
	ds_read_b128 v[46:49], v139 offset:33792
	ds_read_b128 v[184:187], v137 offset:32768
	ds_read_b128 v[188:191], v137 offset:33792
	ds_read_b128 v[196:199], v135 offset:32768
	ds_read_b128 v[204:207], v135 offset:33792
	s_waitcnt vmcnt(2)
	s_setprio 1
	s_barrier
	s_waitcnt lgkmcnt(0)
	v_mfma_f32_16x16x32_bf16 v[74:77], v[10:13], v[26:29], v[126:129]
	v_mfma_f32_16x16x32_bf16 v[126:129], v[14:17], v[30:33], v[74:77]
	v_mfma_f32_16x16x32_bf16 v[74:77], v[180:183], v[26:29], v[122:125]
	v_mfma_f32_16x16x32_bf16 v[122:125], v[144:147], v[30:33], v[74:77]
	v_mfma_f32_16x16x32_bf16 v[74:77], v[10:13], v[42:45], v[118:121]
	v_mfma_f32_16x16x32_bf16 v[110:113], v[14:17], v[46:49], v[74:77]
	v_mfma_f32_16x16x32_bf16 v[74:77], v[180:183], v[42:45], v[114:117]
	v_mfma_f32_16x16x32_bf16 v[106:109], v[144:147], v[46:49], v[74:77]
	v_mfma_f32_16x16x32_bf16 v[74:77], v[10:13], v[184:187], v[130:133]
	v_mfma_f32_16x16x32_bf16 v[94:97], v[14:17], v[188:191], v[74:77]
	v_mfma_f32_16x16x32_bf16 v[74:77], v[180:183], v[184:187], v[148:151]
	v_mfma_f32_16x16x32_bf16 v[90:93], v[144:147], v[188:191], v[74:77]
	v_mfma_f32_16x16x32_bf16 v[74:77], v[10:13], v[196:199], v[102:105]
	v_mfma_f32_16x16x32_bf16 v[78:81], v[14:17], v[204:207], v[74:77]
	v_mfma_f32_16x16x32_bf16 v[74:77], v[180:183], v[196:199], v[98:101]
	v_mfma_f32_16x16x32_bf16 v[74:77], v[144:147], v[204:207], v[74:77]
	s_barrier
;   #define LDA(dst,b,h) for(int m=0;m<4;++m)for(int k=0;k<2;++k) \
;     dst[m][k]=*reinterpret_cast<const bf16x8*>((char*)SA(b,h)+lds_byte(wr*64+m*16+fr,k*32+fq*8))
;   #define LDB(dst,b,h) for(int n=0;n<2;++n)for(int k=0;k<2;++k) \
;     dst[n][k]=*reinterpret_cast<const bf16x8*>((char*)SB(b,h)+lds_byte(wc*32+n*16+fr,k*32+fq*8))
;   #define MMA(ai,bj,At,Bt_) do{__builtin_amdgcn_s_setprio(1); \
;     for(int m=0;m<4;++m)for(int n=0;n<2;++n)for(int k=0;k<2;++k) \
;       acc[ai][bj][m][n]=__builtin_amdgcn_mfma_f32_16x16x32_bf16(Bt_[n][k],At[m][k],acc[ai][bj][m][n],0,0,0); \
;     __builtin_amdgcn_s_setprio(0);}while(0)
;   #define WAIT_V(n) asm volatile("s_waitcnt vmcnt(" #n ")":::"memory")
;   #define WAIT_L(n) asm volatile("s_waitcnt lgkmcnt(" #n ")":::"memory")
;   #define BAR __builtin_amdgcn_s_barrier()
; template <bool TWO, class MID> ...
;     ...
;     LDB(B1,1,1); WAIT_V(0); BAR; WAIT_L(0); MMA(0,1,At,B1); BAR;
;     LDA(At,1,1); BAR; WAIT_L(0); MMA(1,0,At,B0); MMA(1,1,At,B1); BAR; }
;   if(wr==0)BAR;
	s_setprio 0
	ds_read_b128 v[130:133], v143
	ds_read_b128 v[148:151], v143 offset:1024
	ds_read_b128 v[208:211], v143 offset:2048
	ds_read_b128 v[220:223], v143 offset:3072
	s_waitcnt vmcnt(0)
	s_setprio 1
	s_barrier
	s_waitcnt lgkmcnt(0)
	v_mfma_f32_16x16x32_bf16 v[98:101], v[130:133], v[26:29], v[212:215]
	v_mfma_f32_16x16x32_bf16 v[26:29], v[208:211], v[26:29], v[168:171]
	v_mfma_f32_16x16x32_bf16 v[114:117], v[220:223], v[30:33], v[26:29]
	v_mfma_f32_16x16x32_bf16 v[26:29], v[130:133], v[42:45], v[86:89]
	v_mfma_f32_16x16x32_bf16 v[102:105], v[148:151], v[46:49], v[26:29]
	v_mfma_f32_16x16x32_bf16 v[26:29], v[208:211], v[42:45], v[82:85]
	v_mfma_f32_16x16x32_bf16 v[118:121], v[148:151], v[30:33], v[98:101]
	v_mfma_f32_16x16x32_bf16 v[98:101], v[220:223], v[46:49], v[26:29]
	v_mfma_f32_16x16x32_bf16 v[26:29], v[130:133], v[184:187], v[172:175]
	v_mfma_f32_16x16x32_bf16 v[86:89], v[148:151], v[188:191], v[26:29]
	v_mfma_f32_16x16x32_bf16 v[26:29], v[208:211], v[184:187], v[176:179]
	v_mfma_f32_16x16x32_bf16 v[82:85], v[220:223], v[188:191], v[26:29]
	v_mfma_f32_16x16x32_bf16 v[26:29], v[130:133], v[196:199], v[70:73]
	v_mfma_f32_16x16x32_bf16 v[70:73], v[148:151], v[204:207], v[26:29]
	v_mfma_f32_16x16x32_bf16 v[26:29], v[208:211], v[196:199], v[66:69]
	v_mfma_f32_16x16x32_bf16 v[66:69], v[220:223], v[204:207], v[26:29]
	s_barrier
	s_setprio 0
	ds_read_b128 v[168:171], v141 offset:49152
	ds_read_b128 v[140:143], v141 offset:50176
	ds_read_b128 v[172:175], v139 offset:49152
	ds_read_b128 v[176:179], v139 offset:50176
	ds_read_b128 v[184:187], v137 offset:49152
	ds_read_b128 v[136:139], v137 offset:50176
	ds_read_b128 v[188:191], v135 offset:49152
	ds_read_b128 v[196:199], v135 offset:50176
	s_setprio 1
	s_barrier
	s_waitcnt lgkmcnt(0)
	v_mfma_f32_16x16x32_bf16 v[26:29], v[10:13], v[168:171], v[62:65]
	v_mfma_f32_16x16x32_bf16 v[62:65], v[14:17], v[140:143], v[26:29]
	v_mfma_f32_16x16x32_bf16 v[26:29], v[180:183], v[168:171], v[58:61]
	v_mfma_f32_16x16x32_bf16 v[58:61], v[144:147], v[140:143], v[26:29]
	v_mfma_f32_16x16x32_bf16 v[26:29], v[10:13], v[172:175], v[54:57]
	v_mfma_f32_16x16x32_bf16 v[46:49], v[14:17], v[176:179], v[26:29]
	v_mfma_f32_16x16x32_bf16 v[26:29], v[180:183], v[172:175], v[50:53]
	v_mfma_f32_16x16x32_bf16 v[42:45], v[144:147], v[176:179], v[26:29]
	v_mfma_f32_16x16x32_bf16 v[26:29], v[10:13], v[184:187], v[200:203]
	v_mfma_f32_16x16x32_bf16 v[10:13], v[10:13], v[188:191], v[38:41]
	v_mfma_f32_16x16x32_bf16 v[30:33], v[14:17], v[136:139], v[26:29]
	v_mfma_f32_16x16x32_bf16 v[26:29], v[180:183], v[184:187], v[216:219]
	v_mfma_f32_16x16x32_bf16 v[14:17], v[14:17], v[196:199], v[10:13]
	v_mfma_f32_16x16x32_bf16 v[10:13], v[180:183], v[188:191], v[34:37]
	v_mfma_f32_16x16x32_bf16 v[26:29], v[144:147], v[136:139], v[26:29]
	v_mfma_f32_16x16x32_bf16 v[10:13], v[144:147], v[196:199], v[10:13]
	s_setprio 0
	s_setprio 1
	v_mfma_f32_16x16x32_bf16 v[34:37], v[130:133], v[168:171], v[152:155]
	v_mfma_f32_16x16x32_bf16 v[54:57], v[148:151], v[140:143], v[34:37]
	v_mfma_f32_16x16x32_bf16 v[34:37], v[208:211], v[168:171], v[156:159]
	v_mfma_f32_16x16x32_bf16 v[18:21], v[208:211], v[172:175], v[18:21]
	v_mfma_f32_16x16x32_bf16 v[50:53], v[220:223], v[140:143], v[34:37]
	v_mfma_f32_16x16x32_bf16 v[22:25], v[130:133], v[172:175], v[22:25]
	v_mfma_f32_16x16x32_bf16 v[34:37], v[220:223], v[176:179], v[18:21]
	v_mfma_f32_16x16x32_bf16 v[18:21], v[130:133], v[184:187], v[160:163]
	v_mfma_f32_16x16x32_bf16 v[38:41], v[148:151], v[176:179], v[22:25]
	v_mfma_f32_16x16x32_bf16 v[22:25], v[148:151], v[136:139], v[18:21]
	v_mfma_f32_16x16x32_bf16 v[18:21], v[208:211], v[184:187], v[164:167]
	v_mfma_f32_16x16x32_bf16 v[6:9], v[130:133], v[188:191], v[6:9]
	v_mfma_f32_16x16x32_bf16 v[2:5], v[208:211], v[188:191], v[2:5]
	v_mfma_f32_16x16x32_bf16 v[18:21], v[220:223], v[136:139], v[18:21]
	v_mfma_f32_16x16x32_bf16 v[6:9], v[148:151], v[196:199], v[6:9]
	v_mfma_f32_16x16x32_bf16 v[2:5], v[220:223], v[196:199], v[2:5]
	s_setprio 0
	v_cmp_gt_u32_e32 vcc, s30, v1
	s_barrier
	s_and_saveexec_b64 s[0:1], vcc
	s_cbranch_execz .LBB0_623
	s_barrier
